# softmax: running max and its scaled bias rewritten only on the rescale path; row-sum cross-half combine deferred to the pass epilogue
# speedup vs baseline: 1.0141x; 1.0141x over previous
.LBB0_513:
	s_lshl_b32 s4, s76, 14
	v_add3_u32 v236, s4, v221, v220
	ds_read_b128 v[192:195], v236
	ds_read_b128 v[196:199], v236 offset:8192
	v_add3_u32 v236, s4, v222, v220
	ds_read_b128 v[200:203], v236
	ds_read_b128 v[204:207], v236 offset:8192
	v_add3_u32 v236, s4, v223, v220
	ds_read_b128 v[240:243], v236
	ds_read_b128 v[244:247], v236 offset:8192
	v_add3_u32 v236, s4, v224, v220
	ds_read_b128 v[248:251], v236
	ds_read_b128 v[252:255], v236 offset:8192
	s_waitcnt lgkmcnt(7)
	v_mfma_f32_32x32x16_bf16 v[144:159], v[192:195], v[160:163], 0
	s_waitcnt lgkmcnt(6)
	v_mfma_f32_32x32x16_bf16 v[128:143], v[196:199], v[160:163], 0
	v_add3_u32 v236, s4, v225, v220
	ds_read_b128 v[192:195], v236
	ds_read_b128 v[196:199], v236 offset:8192
	s_waitcnt lgkmcnt(7)
	v_mfma_f32_32x32x16_bf16 v[144:159], v[200:203], v[164:167], v[144:159]
	s_waitcnt lgkmcnt(6)
	v_mfma_f32_32x32x16_bf16 v[128:143], v[204:207], v[164:167], v[128:143]
	v_add3_u32 v236, s4, v227, v220
	ds_read_b128 v[200:203], v236
	ds_read_b128 v[204:207], v236 offset:8192
	s_waitcnt lgkmcnt(7)
	v_mfma_f32_32x32x16_bf16 v[144:159], v[240:243], v[168:171], v[144:159]
	s_waitcnt lgkmcnt(6)
	v_mfma_f32_32x32x16_bf16 v[128:143], v[244:247], v[168:171], v[128:143]
	v_add3_u32 v236, s4, v228, v220
	ds_read_b128 v[240:243], v236
	ds_read_b128 v[244:247], v236 offset:8192
	s_waitcnt lgkmcnt(7)
	v_mfma_f32_32x32x16_bf16 v[144:159], v[248:251], v[172:175], v[144:159]
	s_waitcnt lgkmcnt(6)
	v_mfma_f32_32x32x16_bf16 v[128:143], v[252:255], v[172:175], v[128:143]
	v_add3_u32 v236, s4, v229, v220
	ds_read_b128 v[248:251], v236
	ds_read_b128 v[252:255], v236 offset:8192
	s_waitcnt lgkmcnt(7)
	v_mfma_f32_32x32x16_bf16 v[144:159], v[192:195], v[176:179], v[144:159]
	s_waitcnt lgkmcnt(6)
	v_mfma_f32_32x32x16_bf16 v[128:143], v[196:199], v[176:179], v[128:143]
	s_waitcnt lgkmcnt(5)
	v_mfma_f32_32x32x16_bf16 v[144:159], v[200:203], v[180:183], v[144:159]
	s_waitcnt lgkmcnt(4)
	v_mfma_f32_32x32x16_bf16 v[128:143], v[204:207], v[180:183], v[128:143]
	s_waitcnt lgkmcnt(3)
	v_mfma_f32_32x32x16_bf16 v[144:159], v[240:243], v[184:187], v[144:159]
	s_waitcnt lgkmcnt(2)
	v_mfma_f32_32x32x16_bf16 v[128:143], v[244:247], v[184:187], v[128:143]
	s_waitcnt lgkmcnt(1)
	v_mfma_f32_32x32x16_bf16 v[144:159], v[248:251], v[188:191], v[144:159]
	s_waitcnt lgkmcnt(0)
	v_mfma_f32_32x32x16_bf16 v[128:143], v[252:255], v[188:191], v[128:143]
	s_nop 9
	v_max_f32_e32 v192, v144, v145
	v_max3_f32 v192, v192, v146, v147
	v_max3_f32 v192, v192, v148, v149
	v_max3_f32 v192, v192, v150, v151
	v_max3_f32 v192, v192, v152, v153
	v_max3_f32 v192, v192, v154, v155
	v_max3_f32 v192, v192, v156, v157
	v_max3_f32 v192, v192, v158, v159
	v_max3_f32 v192, v192, v128, v129
	v_max3_f32 v192, v192, v130, v131
	v_max3_f32 v192, v192, v132, v133
	v_max3_f32 v192, v192, v134, v135
	v_max3_f32 v192, v192, v136, v137
	v_max3_f32 v192, v192, v138, v139
	v_max3_f32 v192, v192, v140, v141
	v_max3_f32 v192, v192, v142, v143
	v_mov_b32_e32 v193, v192
	s_nop 1
	v_permlane32_swap_b32_e32 v192, v193
	v_max_f32_e32 v192, v192, v193
	v_sub_f32_e32 v193, v192, v231
	v_cmp_ge_f32_e32 vcc, s38, v193
	v_max_f32_e32 v234, v231, v192
	v_sub_f32_e32 v192, v231, v234
	v_mul_f32_e32 v192, 0x3e0293ee, v192
	v_exp_f32_e32 v192, v192
	s_cmp_eq_u64 vcc, exec
	s_cselect_b64 s[4:5], -1, 0
	v_cndmask_b32_e64 v233, v192, 1.0, s[4:5]
	v_cmp_gt_f32_e32 vcc, 1.0, v233
	s_cbranch_vccz .LBB0_517
	v_mov_b32_e32 v231, v234
	v_mul_f32_e32 v237, 0xbe0293ee, v234
	s_and_saveexec_b64 s[24:25], s[0:1]
	ds_write_b32 v226, v233 offset:128
	s_or_b64 exec, exec, s[24:25]
	s_waitcnt lgkmcnt(0)
	v_add_u32_e32 v192, s21, v210
	ds_read_b128 v[204:207], v192 offset:224
	ds_read_b128 v[200:203], v192 offset:192
	ds_read_b128 v[196:199], v192 offset:160
	ds_read_b128 v[192:195], v192 offset:128
	s_waitcnt lgkmcnt(3)
	v_pk_mul_f32 v[12:13], v[12:13], v[204:205]
	s_waitcnt lgkmcnt(2)
	v_pk_mul_f32 v[8:9], v[8:9], v[200:201]
	s_waitcnt lgkmcnt(1)
	v_pk_mul_f32 v[4:5], v[4:5], v[196:197]
	v_pk_mul_f32 v[14:15], v[14:15], v[206:207]
	v_pk_mul_f32 v[10:11], v[10:11], v[202:203]
	v_pk_mul_f32 v[6:7], v[6:7], v[198:199]
	s_waitcnt lgkmcnt(0)
	v_pk_mul_f32 v[2:3], v[2:3], v[194:195]
	v_pk_mul_f32 v[0:1], v[0:1], v[192:193]
	v_pk_mul_f32 v[124:125], v[124:125], v[204:205]
	v_pk_mul_f32 v[120:121], v[120:121], v[200:201]
	v_pk_mul_f32 v[116:117], v[116:117], v[196:197]
	v_pk_mul_f32 v[126:127], v[126:127], v[206:207]
	v_pk_mul_f32 v[122:123], v[122:123], v[202:203]
	v_pk_mul_f32 v[118:119], v[118:119], v[198:199]
	v_pk_mul_f32 v[114:115], v[114:115], v[194:195]
	v_pk_mul_f32 v[112:113], v[112:113], v[192:193]
	v_pk_mul_f32 v[108:109], v[108:109], v[204:205]
	v_pk_mul_f32 v[104:105], v[104:105], v[200:201]
	v_pk_mul_f32 v[100:101], v[100:101], v[196:197]
	v_pk_mul_f32 v[110:111], v[110:111], v[206:207]
	v_pk_mul_f32 v[106:107], v[106:107], v[202:203]
	v_pk_mul_f32 v[102:103], v[102:103], v[198:199]
	v_pk_mul_f32 v[98:99], v[98:99], v[194:195]
	v_pk_mul_f32 v[96:97], v[96:97], v[192:193]
	v_pk_mul_f32 v[92:93], v[92:93], v[204:205]
	v_pk_mul_f32 v[88:89], v[88:89], v[200:201]
	v_pk_mul_f32 v[84:85], v[84:85], v[196:197]
	v_pk_mul_f32 v[94:95], v[94:95], v[206:207]
	v_pk_mul_f32 v[90:91], v[90:91], v[202:203]
	v_pk_mul_f32 v[86:87], v[86:87], v[198:199]
	v_pk_mul_f32 v[82:83], v[82:83], v[194:195]
	v_pk_mul_f32 v[80:81], v[80:81], v[192:193]
	v_pk_mul_f32 v[76:77], v[76:77], v[204:205]
	v_pk_mul_f32 v[72:73], v[72:73], v[200:201]
	v_pk_mul_f32 v[68:69], v[68:69], v[196:197]
	v_pk_mul_f32 v[78:79], v[78:79], v[206:207]
	v_pk_mul_f32 v[74:75], v[74:75], v[202:203]
	v_pk_mul_f32 v[70:71], v[70:71], v[198:199]
	v_pk_mul_f32 v[66:67], v[66:67], v[194:195]
	v_pk_mul_f32 v[64:65], v[64:65], v[192:193]
	v_pk_mul_f32 v[60:61], v[60:61], v[204:205]
	v_pk_mul_f32 v[56:57], v[56:57], v[200:201]
	v_pk_mul_f32 v[52:53], v[52:53], v[196:197]
	v_pk_mul_f32 v[62:63], v[62:63], v[206:207]
	v_pk_mul_f32 v[58:59], v[58:59], v[202:203]
	v_pk_mul_f32 v[54:55], v[54:55], v[198:199]
	v_pk_mul_f32 v[50:51], v[50:51], v[194:195]
	v_pk_mul_f32 v[48:49], v[48:49], v[192:193]
	v_pk_mul_f32 v[44:45], v[44:45], v[204:205]
	v_pk_mul_f32 v[40:41], v[40:41], v[200:201]
	v_pk_mul_f32 v[36:37], v[36:37], v[196:197]
	v_pk_mul_f32 v[46:47], v[46:47], v[206:207]
	v_pk_mul_f32 v[42:43], v[42:43], v[202:203]
	v_pk_mul_f32 v[38:39], v[38:39], v[198:199]
	v_pk_mul_f32 v[34:35], v[34:35], v[194:195]
	v_pk_mul_f32 v[32:33], v[32:33], v[192:193]
	v_pk_mul_f32 v[28:29], v[28:29], v[204:205]
	v_pk_mul_f32 v[24:25], v[24:25], v[200:201]
	v_pk_mul_f32 v[20:21], v[20:21], v[196:197]
	v_pk_mul_f32 v[30:31], v[30:31], v[206:207]
	v_pk_mul_f32 v[26:27], v[26:27], v[202:203]
	v_pk_mul_f32 v[22:23], v[22:23], v[198:199]
	v_pk_mul_f32 v[18:19], v[18:19], v[194:195]
	v_pk_mul_f32 v[16:17], v[16:17], v[192:193]
.LBB0_517:
	v_fmamk_f32 v144, v144, 0x3e0293ee, v237
	v_fmamk_f32 v145, v145, 0x3e0293ee, v237
	v_fmamk_f32 v146, v146, 0x3e0293ee, v237
	v_fmamk_f32 v147, v147, 0x3e0293ee, v237
	v_fmamk_f32 v148, v148, 0x3e0293ee, v237
	v_fmamk_f32 v149, v149, 0x3e0293ee, v237
	v_fmamk_f32 v150, v150, 0x3e0293ee, v237
	v_fmamk_f32 v151, v151, 0x3e0293ee, v237
	v_fmamk_f32 v152, v152, 0x3e0293ee, v237
	v_fmamk_f32 v153, v153, 0x3e0293ee, v237
	v_fmamk_f32 v154, v154, 0x3e0293ee, v237
	v_fmamk_f32 v155, v155, 0x3e0293ee, v237
	v_fmamk_f32 v156, v156, 0x3e0293ee, v237
	v_fmamk_f32 v157, v157, 0x3e0293ee, v237
	v_fmamk_f32 v158, v158, 0x3e0293ee, v237
	v_fmamk_f32 v159, v159, 0x3e0293ee, v237
	v_fmamk_f32 v128, v128, 0x3e0293ee, v237
	v_fmamk_f32 v129, v129, 0x3e0293ee, v237
	v_fmamk_f32 v130, v130, 0x3e0293ee, v237
	v_fmamk_f32 v131, v131, 0x3e0293ee, v237
	v_fmamk_f32 v132, v132, 0x3e0293ee, v237
	v_fmamk_f32 v133, v133, 0x3e0293ee, v237
	v_fmamk_f32 v134, v134, 0x3e0293ee, v237
	v_fmamk_f32 v135, v135, 0x3e0293ee, v237
	v_fmamk_f32 v136, v136, 0x3e0293ee, v237
	v_fmamk_f32 v137, v137, 0x3e0293ee, v237
	v_fmamk_f32 v138, v138, 0x3e0293ee, v237
	v_fmamk_f32 v139, v139, 0x3e0293ee, v237
	v_fmamk_f32 v140, v140, 0x3e0293ee, v237
	v_fmamk_f32 v141, v141, 0x3e0293ee, v237
	v_fmamk_f32 v142, v142, 0x3e0293ee, v237
	v_fmamk_f32 v192, v143, 0x3e0293ee, v237
	v_exp_f32_e32 v143, v144
	v_exp_f32_e32 v145, v145
	v_exp_f32_e32 v146, v146
	v_exp_f32_e32 v147, v147
	v_exp_f32_e32 v148, v148
	v_exp_f32_e32 v193, v128
	v_exp_f32_e32 v149, v149
	v_add_f32_e32 v128, v145, v143
	v_exp_f32_e32 v150, v150
	v_add_f32_e32 v128, v146, v128
	v_exp_f32_e32 v151, v151
	v_add_f32_e32 v128, v147, v128
	v_exp_f32_e32 v152, v152
	v_add_f32_e32 v128, v148, v128
	v_exp_f32_e32 v153, v153
	v_add_f32_e32 v128, v149, v128
	v_exp_f32_e32 v154, v154
	v_add_f32_e32 v128, v150, v128
	v_exp_f32_e32 v155, v155
	v_add_f32_e32 v128, v151, v128
	v_exp_f32_e32 v156, v156
	v_add_f32_e32 v128, v152, v128
	v_exp_f32_e32 v157, v157
	v_add_f32_e32 v128, v153, v128
	v_exp_f32_e32 v158, v158
	v_add_f32_e32 v128, v154, v128
	v_exp_f32_e32 v159, v159
	v_add_f32_e32 v128, v155, v128
	v_add_f32_e32 v128, v156, v128
	v_exp_f32_e32 v194, v129
	v_add_f32_e32 v128, v157, v128
	v_exp_f32_e32 v195, v130
	v_add_f32_e32 v128, v158, v128
	v_exp_f32_e32 v196, v131
	v_add_f32_e32 v128, v159, v128
	v_exp_f32_e32 v197, v132
	v_add_f32_e32 v128, v193, v128
	v_exp_f32_e32 v198, v133
	v_add_f32_e32 v128, v194, v128
	v_exp_f32_e32 v199, v134
	v_add_f32_e32 v128, v195, v128
	v_exp_f32_e32 v135, v135
	v_add_f32_e32 v128, v196, v128
	v_exp_f32_e32 v200, v136
	v_add_f32_e32 v128, v197, v128
	v_exp_f32_e32 v201, v137
	v_add_f32_e32 v128, v198, v128
	v_exp_f32_e32 v202, v138
	v_add_f32_e32 v128, v199, v128
	v_exp_f32_e32 v203, v139
	v_add_f32_e32 v128, v135, v128
	v_exp_f32_e32 v204, v140
	v_add_f32_e32 v128, v200, v128
	v_exp_f32_e32 v205, v141
	v_add_f32_e32 v128, v201, v128
	v_exp_f32_e32 v206, v142
	v_add_f32_e32 v128, v202, v128
	v_exp_f32_e32 v192, v192
	v_add_f32_e32 v128, v203, v128
	v_add_f32_e32 v128, v204, v128
	v_add_f32_e32 v128, v205, v128
	v_add_f32_e32 v128, v206, v128
	v_add_f32_e32 v128, v192, v128
	v_fma_f32 v144, v232, v233, v128
	v_cvt_pk_bf16_f32 v128, v143, v145
	v_cvt_pk_bf16_f32 v129, v146, v147
	v_cvt_pk_bf16_f32 v130, v148, v149
	v_cvt_pk_bf16_f32 v131, v150, v151
	v_cvt_pk_bf16_f32 v136, v152, v153
	v_cvt_pk_bf16_f32 v137, v154, v155
	v_cvt_pk_bf16_f32 v138, v156, v157
	v_cvt_pk_bf16_f32 v139, v158, v159
	v_cvt_pk_bf16_f32 v132, v193, v194
	v_cvt_pk_bf16_f32 v133, v195, v196
	v_cvt_pk_bf16_f32 v134, v197, v198
	v_cvt_pk_bf16_f32 v135, v199, v135
	v_cvt_pk_bf16_f32 v140, v200, v201
	v_cvt_pk_bf16_f32 v141, v202, v203
	v_cvt_pk_bf16_f32 v142, v204, v205
	v_cvt_pk_bf16_f32 v143, v206, v192
	v_lshl_add_u32 v145, s76, 15, v230
	ds_read_b64_tr_b16 v[146:147], v145 offset:0
	ds_read_b64_tr_b16 v[148:149], v145 offset:4096
	ds_read_b64_tr_b16 v[150:151], v145 offset:512
	ds_read_b64_tr_b16 v[152:153], v145 offset:4608
	ds_read_b64_tr_b16 v[154:155], v145 offset:1024
	ds_read_b64_tr_b16 v[156:157], v145 offset:5120
	ds_read_b64_tr_b16 v[192:193], v145 offset:1536
	ds_read_b64_tr_b16 v[194:195], v145 offset:5632
	ds_read_b64_tr_b16 v[196:197], v145 offset:2048
	ds_read_b64_tr_b16 v[198:199], v145 offset:6144
	ds_read_b64_tr_b16 v[200:201], v145 offset:2560
	ds_read_b64_tr_b16 v[202:203], v145 offset:6656
	ds_read_b64_tr_b16 v[204:205], v145 offset:3072
	ds_read_b64_tr_b16 v[206:207], v145 offset:7168
	s_waitcnt lgkmcnt(12)
	s_nop 0
	v_mfma_f32_32x32x16_bf16 v[0:15], v[128:131], v[146:149], v[0:15]
	ds_read_b64_tr_b16 v[232:233], v145 offset:3584
	ds_read_b64_tr_b16 v[234:235], v145 offset:7680
	s_waitcnt lgkmcnt(12)
	v_mfma_f32_32x32x16_bf16 v[112:127], v[128:131], v[150:153], v[112:127]
	ds_read_b64_tr_b16 v[146:147], v145 offset:8192
	ds_read_b64_tr_b16 v[148:149], v145 offset:12288
	s_waitcnt lgkmcnt(12)
	v_mfma_f32_32x32x16_bf16 v[96:111], v[128:131], v[154:157], v[96:111]
	ds_read_b64_tr_b16 v[150:151], v145 offset:8704
	ds_read_b64_tr_b16 v[152:153], v145 offset:12800
	s_waitcnt lgkmcnt(12)
	v_mfma_f32_32x32x16_bf16 v[80:95], v[128:131], v[192:195], v[80:95]
	ds_read_b64_tr_b16 v[154:155], v145 offset:9216
	ds_read_b64_tr_b16 v[156:157], v145 offset:13312
	s_waitcnt lgkmcnt(12)
	v_mfma_f32_32x32x16_bf16 v[64:79], v[128:131], v[196:199], v[64:79]
	ds_read_b64_tr_b16 v[192:193], v145 offset:9728
	ds_read_b64_tr_b16 v[194:195], v145 offset:13824
	s_waitcnt lgkmcnt(12)
	v_mfma_f32_32x32x16_bf16 v[48:63], v[128:131], v[200:203], v[48:63]
	ds_read_b64_tr_b16 v[196:197], v145 offset:10240
	ds_read_b64_tr_b16 v[198:199], v145 offset:14336
	s_waitcnt lgkmcnt(12)
	v_mfma_f32_32x32x16_bf16 v[32:47], v[128:131], v[204:207], v[32:47]
	ds_read_b64_tr_b16 v[200:201], v145 offset:10752
	ds_read_b64_tr_b16 v[202:203], v145 offset:14848
	s_waitcnt lgkmcnt(12)
	v_mfma_f32_32x32x16_bf16 v[16:31], v[128:131], v[232:235], v[16:31]
	ds_read_b64_tr_b16 v[204:205], v145 offset:11264
	ds_read_b64_tr_b16 v[206:207], v145 offset:15360
	s_waitcnt lgkmcnt(12)
	v_mfma_f32_32x32x16_bf16 v[0:15], v[136:139], v[146:149], v[0:15]
	ds_read_b64_tr_b16 v[232:233], v145 offset:11776
	ds_read_b64_tr_b16 v[234:235], v145 offset:15872
	s_waitcnt lgkmcnt(12)
	v_mfma_f32_32x32x16_bf16 v[112:127], v[136:139], v[150:153], v[112:127]
	ds_read_b64_tr_b16 v[146:147], v145 offset:16384
	ds_read_b64_tr_b16 v[148:149], v145 offset:20480
	s_waitcnt lgkmcnt(12)
	v_mfma_f32_32x32x16_bf16 v[96:111], v[136:139], v[154:157], v[96:111]
	ds_read_b64_tr_b16 v[150:151], v145 offset:16896
	ds_read_b64_tr_b16 v[152:153], v145 offset:20992
	s_waitcnt lgkmcnt(12)
	v_mfma_f32_32x32x16_bf16 v[80:95], v[136:139], v[192:195], v[80:95]
	ds_read_b64_tr_b16 v[154:155], v145 offset:17408
	ds_read_b64_tr_b16 v[156:157], v145 offset:21504
	s_waitcnt lgkmcnt(12)
	v_mfma_f32_32x32x16_bf16 v[64:79], v[136:139], v[196:199], v[64:79]
	ds_read_b64_tr_b16 v[192:193], v145 offset:17920
	ds_read_b64_tr_b16 v[194:195], v145 offset:22016
	s_waitcnt lgkmcnt(12)
	v_mfma_f32_32x32x16_bf16 v[48:63], v[136:139], v[200:203], v[48:63]
	ds_read_b64_tr_b16 v[196:197], v145 offset:18432
	ds_read_b64_tr_b16 v[198:199], v145 offset:22528
	s_waitcnt lgkmcnt(12)
	v_mfma_f32_32x32x16_bf16 v[32:47], v[136:139], v[204:207], v[32:47]
	ds_read_b64_tr_b16 v[200:201], v145 offset:18944
	ds_read_b64_tr_b16 v[202:203], v145 offset:23040
	s_waitcnt lgkmcnt(12)
	v_mfma_f32_32x32x16_bf16 v[16:31], v[136:139], v[232:235], v[16:31]
	ds_read_b64_tr_b16 v[204:205], v145 offset:19456
	ds_read_b64_tr_b16 v[206:207], v145 offset:23552
	s_waitcnt lgkmcnt(12)
	v_mfma_f32_32x32x16_bf16 v[0:15], v[132:135], v[146:149], v[0:15]
	ds_read_b64_tr_b16 v[232:233], v145 offset:19968
	ds_read_b64_tr_b16 v[234:235], v145 offset:24064
	s_waitcnt lgkmcnt(12)
	v_mfma_f32_32x32x16_bf16 v[112:127], v[132:135], v[150:153], v[112:127]
	ds_read_b64_tr_b16 v[146:147], v145 offset:24576
	ds_read_b64_tr_b16 v[148:149], v145 offset:28672
	s_waitcnt lgkmcnt(12)
	v_mfma_f32_32x32x16_bf16 v[96:111], v[132:135], v[154:157], v[96:111]
	ds_read_b64_tr_b16 v[150:151], v145 offset:25088
	ds_read_b64_tr_b16 v[152:153], v145 offset:29184
	s_waitcnt lgkmcnt(12)
	v_mfma_f32_32x32x16_bf16 v[80:95], v[132:135], v[192:195], v[80:95]
	ds_read_b64_tr_b16 v[154:155], v145 offset:25600
	ds_read_b64_tr_b16 v[156:157], v145 offset:29696
	s_waitcnt lgkmcnt(12)
	v_mfma_f32_32x32x16_bf16 v[64:79], v[132:135], v[196:199], v[64:79]
	ds_read_b64_tr_b16 v[192:193], v145 offset:26112
	ds_read_b64_tr_b16 v[194:195], v145 offset:30208
	s_waitcnt lgkmcnt(12)
	v_mfma_f32_32x32x16_bf16 v[48:63], v[132:135], v[200:203], v[48:63]
	ds_read_b64_tr_b16 v[196:197], v145 offset:26624
	ds_read_b64_tr_b16 v[198:199], v145 offset:30720
	s_waitcnt lgkmcnt(12)
	v_mfma_f32_32x32x16_bf16 v[32:47], v[132:135], v[204:207], v[32:47]
	ds_read_b64_tr_b16 v[200:201], v145 offset:27136
	ds_read_b64_tr_b16 v[202:203], v145 offset:31232
	s_waitcnt lgkmcnt(12)
	v_mfma_f32_32x32x16_bf16 v[16:31], v[132:135], v[232:235], v[16:31]
	ds_read_b64_tr_b16 v[204:205], v145 offset:27648
	ds_read_b64_tr_b16 v[206:207], v145 offset:31744
	s_waitcnt lgkmcnt(12)
	v_mfma_f32_32x32x16_bf16 v[0:15], v[140:143], v[146:149], v[0:15]
	ds_read_b64_tr_b16 v[232:233], v145 offset:28160
	ds_read_b64_tr_b16 v[234:235], v145 offset:32256
	s_waitcnt lgkmcnt(12)
	v_mfma_f32_32x32x16_bf16 v[112:127], v[140:143], v[150:153], v[112:127]
	s_waitcnt lgkmcnt(10)
	v_mfma_f32_32x32x16_bf16 v[96:111], v[140:143], v[154:157], v[96:111]
	s_waitcnt lgkmcnt(8)
	v_mfma_f32_32x32x16_bf16 v[80:95], v[140:143], v[192:195], v[80:95]
	s_waitcnt lgkmcnt(6)
	v_mfma_f32_32x32x16_bf16 v[64:79], v[140:143], v[196:199], v[64:79]
	s_add_i32 s4, s76, 1
	s_cmp_lg_u32 s76, 2
	s_cselect_b32 s76, s4, 0
	s_add_i32 s4, s74, 1
	s_cmp_lg_u32 s74, 2
	s_cselect_b32 s74, s4, 0
	s_add_u32 s22, s22, 0x20000
	s_waitcnt lgkmcnt(4)
	v_mfma_f32_32x32x16_bf16 v[48:63], v[140:143], v[200:203], v[48:63]
	s_addc_u32 s23, s23, 0
	s_add_i32 s86, s86, 1
	s_cmp_eq_u32 s22, 0x800000
	s_waitcnt lgkmcnt(2)
	v_mfma_f32_32x32x16_bf16 v[32:47], v[140:143], v[204:207], v[32:47]
	s_waitcnt lgkmcnt(0)
	v_mfma_f32_32x32x16_bf16 v[16:31], v[140:143], v[232:235], v[16:31]
	s_cbranch_scc1 .LBB0_521
	v_mov_b32_e32 v232, v144
	s_cmp_eq_u32 s22, 0x7e0000
	s_mov_b64 s[4:5], -1
	s_cbranch_scc1 .LBB0_510

.LBB0_521:
	v_mov_b32_e32 v129, v144
	s_nop 1
	v_permlane32_swap_b32_e32 v144, v129
	v_add_f32_e32 v144, v144, v129
	s_and_saveexec_b64 s[4:5], s[0:1]
	ds_write_b32 v226, v144
	s_or_b64 exec, exec, s[4:5]
	s_waitcnt lgkmcnt(0)
	v_add_u32_e32 v136, s21, v210
	ds_read_b128 v[128:131], v136
	ds_read_b128 v[132:135], v136 offset:32
	s_ashr_i32 s21, s20, 31
	s_lshl_b64 s[0:1], s[20:21], 12
	ds_read_b128 v[138:141], v136 offset:96
	s_waitcnt lgkmcnt(2)
	v_rcp_f32_e32 v142, v128
	v_rcp_f32_e32 v145, v129
	v_rcp_f32_e32 v152, v130
	v_rcp_f32_e32 v161, v131
	ds_read_b128 v[128:131], v136 offset:64
	s_waitcnt lgkmcnt(2)
	v_rcp_f32_e32 v162, v132
	v_rcp_f32_e32 v163, v133
	v_rcp_f32_e32 v164, v134
	v_rcp_f32_e32 v165, v135
	s_waitcnt lgkmcnt(0)
	v_rcp_f32_e32 v137, v128
	v_rcp_f32_e32 v136, v129
	v_rcp_f32_e32 v135, v130
	v_rcp_f32_e32 v134, v131
	v_rcp_f32_e32 v133, v138
	v_rcp_f32_e32 v132, v139
	v_rcp_f32_e32 v131, v140
	v_rcp_f32_e32 v130, v141
	s_add_u32 s0, s62, s0
	s_addc_u32 s1, s63, s1
	s_mov_b64 s[4:5], -1
	s_andn2_b64 vcc, exec, s[18:19]
	v_lshlrev_b32_e32 v210, 2, v219
	v_lshlrev_b32_e32 v128, 14, v218
	v_lshl_add_u32 v129, v218, 5, v219
	v_lshlrev_b32_e32 v128, 4, v129
	s_mov_b32 s96, s0
	s_mov_b32 s97, s1
	s_cbranch_vccnz .Lepi0_p0
	s_lshl_b64 s[4:5], s[20:21], 11
	s_add_u32 s4, s64, s4
	s_addc_u32 s5, s65, s5
	v_lshlrev_b32_e32 v140, 1, v219
	v_lshl_add_u32 v140, v218, 13, v140
	v_mov_b32_e32 v141, 0
	v_lshl_add_u64 v[146:147], s[4:5], 0, v[140:141]
	s_mov_b64 s[100:101], 0x1000
	s_mov_b64 s[98:99], 0x4000
	global_load_dwordx4 v[166:169], v128, s[96:97]
	s_add_u32 s96, s96, 0x1000
	s_addc_u32 s97, s97, 0
	global_load_dwordx4 v[170:173], v128, s[96:97]
	s_add_u32 s96, s96, 0x1000
	s_addc_u32 s97, s97, 0
	global_load_dwordx4 v[174:177], v128, s[96:97]
	s_add_u32 s96, s96, 0x1000
	s_addc_u32 s97, s97, 0
	global_load_dwordx4 v[178:181], v128, s[96:97]
	s_add_u32 s96, s96, 0x1000
	s_addc_u32 s97, s97, 0
	global_load_dwordx4 v[182:185], v128, s[96:97]
	s_add_u32 s96, s96, 0x1000
	s_addc_u32 s97, s97, 0
	global_load_dwordx4 v[186:189], v128, s[96:97]
	s_add_u32 s96, s96, 0x1000
	s_addc_u32 s97, s97, 0
	global_load_dwordx4 v[190:193], v128, s[96:97]
	s_add_u32 s96, s96, 0x1000
	s_addc_u32 s97, s97, 0
	global_load_dwordx4 v[194:197], v128, s[96:97]
	s_add_u32 s96, s96, 0x1000
	s_addc_u32 s97, s97, 0
	global_load_dwordx4 v[198:201], v128, s[96:97]
	s_add_u32 s96, s96, 0x1000
	s_addc_u32 s97, s97, 0
	global_load_dwordx4 v[202:205], v128, s[96:97]
	s_add_u32 s96, s96, 0x1000
	s_addc_u32 s97, s97, 0
	global_load_dwordx4 v[240:243], v128, s[96:97]
	s_add_u32 s96, s96, 0x1000
	s_addc_u32 s97, s97, 0
	global_load_dwordx4 v[244:247], v128, s[96:97]
	s_add_u32 s96, s96, 0x1000
	s_addc_u32 s97, s97, 0
	global_load_dwordx4 v[248:251], v128, s[96:97]
	s_add_u32 s96, s96, 0x1000
	s_addc_u32 s97, s97, 0
	global_load_dwordx4 v[252:255], v128, s[96:97]
	s_add_u32 s96, s96, 0x1000
	s_addc_u32 s97, s97, 0
	global_load_dwordx4 v[232:235], v128, s[96:97]
	s_add_u32 s96, s96, 0x1000
	s_addc_u32 s97, s97, 0
	global_load_dwordx4 v[154:157], v128, s[96:97]
	s_add_u32 s96, s96, 0x1000
	s_addc_u32 s97, s97, 0
	s_waitcnt vmcnt(8)
	v_lshl_add_u64 v[148:149], v[146:147], 0, s[100:101]
	v_mul_f32_e32 v158, v0, v142
	v_fma_f32 v166, -v209, v158, v166
	v_bfe_u32 v158, v166, 16, 1
	v_add3_u32 v166, v166, v158, s39
	global_store_short_d16_hi v[146:147], v166, off
	v_mul_f32_e32 v159, v1, v145
	v_fma_f32 v167, -v209, v159, v167
	v_bfe_u32 v159, v167, 16, 1
	v_add3_u32 v167, v167, v159, s39
	global_store_short_d16_hi v[146:147], v167, off offset:2048
	v_mul_f32_e32 v160, v2, v152
	v_fma_f32 v168, -v209, v160, v168
	v_bfe_u32 v160, v168, 16, 1
	v_add3_u32 v168, v168, v160, s39
	global_store_short_d16_hi v[148:149], v168, off
	v_mul_f32_e32 v150, v3, v161
	v_fma_f32 v169, -v209, v150, v169
	v_bfe_u32 v150, v169, 16, 1
	v_add3_u32 v169, v169, v150, s39
	global_store_short_d16_hi v[148:149], v169, off offset:2048
	v_mul_f32_e32 v158, v112, v142
	v_fma_f32 v170, -v209, v158, v170
	v_bfe_u32 v158, v170, 16, 1
	v_add3_u32 v170, v170, v158, s39
	global_store_short_d16_hi v[146:147], v170, off offset:64
	v_mul_f32_e32 v159, v113, v145
	v_fma_f32 v171, -v209, v159, v171
	v_bfe_u32 v159, v171, 16, 1
	v_add3_u32 v171, v171, v159, s39
	global_store_short_d16_hi v[146:147], v171, off offset:2112
	v_mul_f32_e32 v160, v114, v152
	v_fma_f32 v172, -v209, v160, v172
	v_bfe_u32 v160, v172, 16, 1
	v_add3_u32 v172, v172, v160, s39
	global_store_short_d16_hi v[148:149], v172, off offset:64
	v_mul_f32_e32 v150, v115, v161
	v_fma_f32 v173, -v209, v150, v173
	v_bfe_u32 v150, v173, 16, 1
	v_add3_u32 v173, v173, v150, s39
	global_store_short_d16_hi v[148:149], v173, off offset:2112
	v_mul_f32_e32 v158, v96, v142
	v_fma_f32 v174, -v209, v158, v174
	v_bfe_u32 v158, v174, 16, 1
	v_add3_u32 v174, v174, v158, s39
	global_store_short_d16_hi v[146:147], v174, off offset:128
	v_mul_f32_e32 v159, v97, v145
	v_fma_f32 v175, -v209, v159, v175
	v_bfe_u32 v159, v175, 16, 1
	v_add3_u32 v175, v175, v159, s39
	global_store_short_d16_hi v[146:147], v175, off offset:2176
	v_mul_f32_e32 v160, v98, v152
	v_fma_f32 v176, -v209, v160, v176
	v_bfe_u32 v160, v176, 16, 1
	v_add3_u32 v176, v176, v160, s39
	global_store_short_d16_hi v[148:149], v176, off offset:128
	v_mul_f32_e32 v150, v99, v161
	v_fma_f32 v177, -v209, v150, v177
	v_bfe_u32 v150, v177, 16, 1
	v_add3_u32 v177, v177, v150, s39
	global_store_short_d16_hi v[148:149], v177, off offset:2176
	v_mul_f32_e32 v158, v80, v142
	v_fma_f32 v178, -v209, v158, v178
	v_bfe_u32 v158, v178, 16, 1
	v_add3_u32 v178, v178, v158, s39
	global_store_short_d16_hi v[146:147], v178, off offset:192
	v_mul_f32_e32 v159, v81, v145
	v_fma_f32 v179, -v209, v159, v179
	v_bfe_u32 v159, v179, 16, 1
	v_add3_u32 v179, v179, v159, s39
	global_store_short_d16_hi v[146:147], v179, off offset:2240
	v_mul_f32_e32 v160, v82, v152
	v_fma_f32 v180, -v209, v160, v180
	v_bfe_u32 v160, v180, 16, 1
	v_add3_u32 v180, v180, v160, s39
	global_store_short_d16_hi v[148:149], v180, off offset:192
	v_mul_f32_e32 v150, v83, v161
	v_fma_f32 v181, -v209, v150, v181
	v_bfe_u32 v150, v181, 16, 1
	v_add3_u32 v181, v181, v150, s39
	global_store_short_d16_hi v[148:149], v181, off offset:2240
	v_mul_f32_e32 v158, v64, v142
	v_fma_f32 v182, -v209, v158, v182
	v_bfe_u32 v158, v182, 16, 1
	v_add3_u32 v182, v182, v158, s39
	global_store_short_d16_hi v[146:147], v182, off offset:256
	v_mul_f32_e32 v159, v65, v145
	v_fma_f32 v183, -v209, v159, v183
	v_bfe_u32 v159, v183, 16, 1
	v_add3_u32 v183, v183, v159, s39
	global_store_short_d16_hi v[146:147], v183, off offset:2304
	v_mul_f32_e32 v160, v66, v152
	v_fma_f32 v184, -v209, v160, v184
	v_bfe_u32 v160, v184, 16, 1
	v_add3_u32 v184, v184, v160, s39
	global_store_short_d16_hi v[148:149], v184, off offset:256
	v_mul_f32_e32 v150, v67, v161
	v_fma_f32 v185, -v209, v150, v185
	v_bfe_u32 v150, v185, 16, 1
	v_add3_u32 v185, v185, v150, s39
	global_store_short_d16_hi v[148:149], v185, off offset:2304
	v_mul_f32_e32 v158, v48, v142
	v_fma_f32 v186, -v209, v158, v186
	v_bfe_u32 v158, v186, 16, 1
	v_add3_u32 v186, v186, v158, s39
	global_store_short_d16_hi v[146:147], v186, off offset:320
	v_mul_f32_e32 v159, v49, v145
	v_fma_f32 v187, -v209, v159, v187
	v_bfe_u32 v159, v187, 16, 1
	v_add3_u32 v187, v187, v159, s39
	global_store_short_d16_hi v[146:147], v187, off offset:2368
	v_mul_f32_e32 v160, v50, v152
	v_fma_f32 v188, -v209, v160, v188
	v_bfe_u32 v160, v188, 16, 1
	v_add3_u32 v188, v188, v160, s39
	global_store_short_d16_hi v[148:149], v188, off offset:320
	v_mul_f32_e32 v150, v51, v161
	v_fma_f32 v189, -v209, v150, v189
	v_bfe_u32 v150, v189, 16, 1
	v_add3_u32 v189, v189, v150, s39
	global_store_short_d16_hi v[148:149], v189, off offset:2368
	v_mul_f32_e32 v158, v32, v142
	v_fma_f32 v190, -v209, v158, v190
	v_bfe_u32 v158, v190, 16, 1
	v_add3_u32 v190, v190, v158, s39
	global_store_short_d16_hi v[146:147], v190, off offset:384
	v_mul_f32_e32 v159, v33, v145
	v_fma_f32 v191, -v209, v159, v191
	v_bfe_u32 v159, v191, 16, 1
	v_add3_u32 v191, v191, v159, s39
	global_store_short_d16_hi v[146:147], v191, off offset:2432
	v_mul_f32_e32 v160, v34, v152
	v_fma_f32 v192, -v209, v160, v192
	v_bfe_u32 v160, v192, 16, 1
	v_add3_u32 v192, v192, v160, s39
	global_store_short_d16_hi v[148:149], v192, off offset:384
	v_mul_f32_e32 v150, v35, v161
	v_fma_f32 v193, -v209, v150, v193
	v_bfe_u32 v150, v193, 16, 1
	v_add3_u32 v193, v193, v150, s39
	global_store_short_d16_hi v[148:149], v193, off offset:2432
	v_mul_f32_e32 v158, v16, v142
	v_fma_f32 v194, -v209, v158, v194
	v_bfe_u32 v158, v194, 16, 1
	v_add3_u32 v194, v194, v158, s39
	global_store_short_d16_hi v[146:147], v194, off offset:448
	v_mul_f32_e32 v159, v17, v145
	v_fma_f32 v195, -v209, v159, v195
	v_bfe_u32 v159, v195, 16, 1
	v_add3_u32 v195, v195, v159, s39
	global_store_short_d16_hi v[146:147], v195, off offset:2496
	v_mul_f32_e32 v160, v18, v152
	v_fma_f32 v196, -v209, v160, v196
	v_bfe_u32 v160, v196, 16, 1
	v_add3_u32 v196, v196, v160, s39
	global_store_short_d16_hi v[148:149], v196, off offset:448
	v_mul_f32_e32 v150, v19, v161
	v_fma_f32 v197, -v209, v150, v197
	v_bfe_u32 v150, v197, 16, 1
	v_add3_u32 v197, v197, v150, s39
	global_store_short_d16_hi v[148:149], v197, off offset:2496
	global_load_dwordx4 v[166:169], v128, s[96:97]
	s_add_u32 s96, s96, 0x1000
	s_addc_u32 s97, s97, 0
	global_load_dwordx4 v[170:173], v128, s[96:97]
	s_add_u32 s96, s96, 0x1000
	s_addc_u32 s97, s97, 0
	global_load_dwordx4 v[174:177], v128, s[96:97]
	s_add_u32 s96, s96, 0x1000
	s_addc_u32 s97, s97, 0
	global_load_dwordx4 v[178:181], v128, s[96:97]
	s_add_u32 s96, s96, 0x1000
	s_addc_u32 s97, s97, 0
	global_load_dwordx4 v[182:185], v128, s[96:97]
	s_add_u32 s96, s96, 0x1000
	s_addc_u32 s97, s97, 0
	global_load_dwordx4 v[186:189], v128, s[96:97]
	s_add_u32 s96, s96, 0x1000
	s_addc_u32 s97, s97, 0
	global_load_dwordx4 v[190:193], v128, s[96:97]
	s_add_u32 s96, s96, 0x1000
	s_addc_u32 s97, s97, 0
	global_load_dwordx4 v[194:197], v128, s[96:97]
	s_add_u32 s96, s96, 0x1000
	s_addc_u32 s97, s97, 0
	v_lshl_add_u64 v[146:147], v[146:147], 0, s[98:99]
	s_waitcnt vmcnt(40)
	v_lshl_add_u64 v[148:149], v[146:147], 0, s[100:101]
	v_mul_f32_e32 v158, v4, v162
	v_fma_f32 v198, -v209, v158, v198
	v_bfe_u32 v158, v198, 16, 1
	v_add3_u32 v198, v198, v158, s39
	global_store_short_d16_hi v[146:147], v198, off
	v_mul_f32_e32 v159, v5, v163
	v_fma_f32 v199, -v209, v159, v199
	v_bfe_u32 v159, v199, 16, 1
	v_add3_u32 v199, v199, v159, s39
	global_store_short_d16_hi v[146:147], v199, off offset:2048
	v_mul_f32_e32 v160, v6, v164
	v_fma_f32 v200, -v209, v160, v200
	v_bfe_u32 v160, v200, 16, 1
	v_add3_u32 v200, v200, v160, s39
	global_store_short_d16_hi v[148:149], v200, off
	v_mul_f32_e32 v150, v7, v165
	v_fma_f32 v201, -v209, v150, v201
	v_bfe_u32 v150, v201, 16, 1
	v_add3_u32 v201, v201, v150, s39
	global_store_short_d16_hi v[148:149], v201, off offset:2048
	v_mul_f32_e32 v158, v116, v162
	v_fma_f32 v202, -v209, v158, v202
	v_bfe_u32 v158, v202, 16, 1
	v_add3_u32 v202, v202, v158, s39
	global_store_short_d16_hi v[146:147], v202, off offset:64
	v_mul_f32_e32 v159, v117, v163
	v_fma_f32 v203, -v209, v159, v203
	v_bfe_u32 v159, v203, 16, 1
	v_add3_u32 v203, v203, v159, s39
	global_store_short_d16_hi v[146:147], v203, off offset:2112
	v_mul_f32_e32 v160, v118, v164
	v_fma_f32 v204, -v209, v160, v204
	v_bfe_u32 v160, v204, 16, 1
	v_add3_u32 v204, v204, v160, s39
	global_store_short_d16_hi v[148:149], v204, off offset:64
	v_mul_f32_e32 v150, v119, v165
	v_fma_f32 v205, -v209, v150, v205
	v_bfe_u32 v150, v205, 16, 1
	v_add3_u32 v205, v205, v150, s39
	global_store_short_d16_hi v[148:149], v205, off offset:2112
	v_mul_f32_e32 v158, v100, v162
	v_fma_f32 v240, -v209, v158, v240
	v_bfe_u32 v158, v240, 16, 1
	v_add3_u32 v240, v240, v158, s39
	global_store_short_d16_hi v[146:147], v240, off offset:128
	v_mul_f32_e32 v159, v101, v163
	v_fma_f32 v241, -v209, v159, v241
	v_bfe_u32 v159, v241, 16, 1
	v_add3_u32 v241, v241, v159, s39
	global_store_short_d16_hi v[146:147], v241, off offset:2176
	v_mul_f32_e32 v160, v102, v164
	v_fma_f32 v242, -v209, v160, v242
	v_bfe_u32 v160, v242, 16, 1
	v_add3_u32 v242, v242, v160, s39
	global_store_short_d16_hi v[148:149], v242, off offset:128
	v_mul_f32_e32 v150, v103, v165
	v_fma_f32 v243, -v209, v150, v243
	v_bfe_u32 v150, v243, 16, 1
	v_add3_u32 v243, v243, v150, s39
	global_store_short_d16_hi v[148:149], v243, off offset:2176
	v_mul_f32_e32 v158, v84, v162
	v_fma_f32 v244, -v209, v158, v244
	v_bfe_u32 v158, v244, 16, 1
	v_add3_u32 v244, v244, v158, s39
	global_store_short_d16_hi v[146:147], v244, off offset:192
	v_mul_f32_e32 v159, v85, v163
	v_fma_f32 v245, -v209, v159, v245
	v_bfe_u32 v159, v245, 16, 1
	v_add3_u32 v245, v245, v159, s39
	global_store_short_d16_hi v[146:147], v245, off offset:2240
	v_mul_f32_e32 v160, v86, v164
	v_fma_f32 v246, -v209, v160, v246
	v_bfe_u32 v160, v246, 16, 1
	v_add3_u32 v246, v246, v160, s39
	global_store_short_d16_hi v[148:149], v246, off offset:192
	v_mul_f32_e32 v150, v87, v165
	v_fma_f32 v247, -v209, v150, v247
	v_bfe_u32 v150, v247, 16, 1
	v_add3_u32 v247, v247, v150, s39
	global_store_short_d16_hi v[148:149], v247, off offset:2240
	v_mul_f32_e32 v158, v68, v162
	v_fma_f32 v248, -v209, v158, v248
	v_bfe_u32 v158, v248, 16, 1
	v_add3_u32 v248, v248, v158, s39
	global_store_short_d16_hi v[146:147], v248, off offset:256
	v_mul_f32_e32 v159, v69, v163
	v_fma_f32 v249, -v209, v159, v249
	v_bfe_u32 v159, v249, 16, 1
	v_add3_u32 v249, v249, v159, s39
	global_store_short_d16_hi v[146:147], v249, off offset:2304
	v_mul_f32_e32 v160, v70, v164
	v_fma_f32 v250, -v209, v160, v250
	v_bfe_u32 v160, v250, 16, 1
	v_add3_u32 v250, v250, v160, s39
	global_store_short_d16_hi v[148:149], v250, off offset:256
	v_mul_f32_e32 v150, v71, v165
	v_fma_f32 v251, -v209, v150, v251
	v_bfe_u32 v150, v251, 16, 1
	v_add3_u32 v251, v251, v150, s39
	global_store_short_d16_hi v[148:149], v251, off offset:2304
	v_mul_f32_e32 v158, v52, v162
	v_fma_f32 v252, -v209, v158, v252
	v_bfe_u32 v158, v252, 16, 1
	v_add3_u32 v252, v252, v158, s39
	global_store_short_d16_hi v[146:147], v252, off offset:320
	v_mul_f32_e32 v159, v53, v163
	v_fma_f32 v253, -v209, v159, v253
	v_bfe_u32 v159, v253, 16, 1
	v_add3_u32 v253, v253, v159, s39
	global_store_short_d16_hi v[146:147], v253, off offset:2368
	v_mul_f32_e32 v160, v54, v164
	v_fma_f32 v254, -v209, v160, v254
	v_bfe_u32 v160, v254, 16, 1
	v_add3_u32 v254, v254, v160, s39
	global_store_short_d16_hi v[148:149], v254, off offset:320
	v_mul_f32_e32 v150, v55, v165
	v_fma_f32 v255, -v209, v150, v255
	v_bfe_u32 v150, v255, 16, 1
	v_add3_u32 v255, v255, v150, s39
	global_store_short_d16_hi v[148:149], v255, off offset:2368
	v_mul_f32_e32 v158, v36, v162
	v_fma_f32 v232, -v209, v158, v232
	v_bfe_u32 v158, v232, 16, 1
	v_add3_u32 v232, v232, v158, s39
	global_store_short_d16_hi v[146:147], v232, off offset:384
	v_mul_f32_e32 v159, v37, v163
	v_fma_f32 v233, -v209, v159, v233
	v_bfe_u32 v159, v233, 16, 1
	v_add3_u32 v233, v233, v159, s39
	global_store_short_d16_hi v[146:147], v233, off offset:2432
	v_mul_f32_e32 v160, v38, v164
	v_fma_f32 v234, -v209, v160, v234
	v_bfe_u32 v160, v234, 16, 1
	v_add3_u32 v234, v234, v160, s39
	global_store_short_d16_hi v[148:149], v234, off offset:384
	v_mul_f32_e32 v150, v39, v165
	v_fma_f32 v235, -v209, v150, v235
	v_bfe_u32 v150, v235, 16, 1
	v_add3_u32 v235, v235, v150, s39
	global_store_short_d16_hi v[148:149], v235, off offset:2432
	v_mul_f32_e32 v158, v20, v162
	v_fma_f32 v154, -v209, v158, v154
	v_bfe_u32 v158, v154, 16, 1
	v_add3_u32 v154, v154, v158, s39
	global_store_short_d16_hi v[146:147], v154, off offset:448
	v_mul_f32_e32 v159, v21, v163
	v_fma_f32 v155, -v209, v159, v155
	v_bfe_u32 v159, v155, 16, 1
	v_add3_u32 v155, v155, v159, s39
	global_store_short_d16_hi v[146:147], v155, off offset:2496
	v_mul_f32_e32 v160, v22, v164
	v_fma_f32 v156, -v209, v160, v156
	v_bfe_u32 v160, v156, 16, 1
	v_add3_u32 v156, v156, v160, s39
	global_store_short_d16_hi v[148:149], v156, off offset:448
	v_mul_f32_e32 v150, v23, v165
	v_fma_f32 v157, -v209, v150, v157
	v_bfe_u32 v150, v157, 16, 1
	v_add3_u32 v157, v157, v150, s39
	global_store_short_d16_hi v[148:149], v157, off offset:2496
	global_load_dwordx4 v[198:201], v128, s[96:97]
	s_add_u32 s96, s96, 0x1000
	s_addc_u32 s97, s97, 0
	global_load_dwordx4 v[202:205], v128, s[96:97]
	s_add_u32 s96, s96, 0x1000
	s_addc_u32 s97, s97, 0
	global_load_dwordx4 v[240:243], v128, s[96:97]
	s_add_u32 s96, s96, 0x1000
	s_addc_u32 s97, s97, 0
	global_load_dwordx4 v[244:247], v128, s[96:97]
	s_add_u32 s96, s96, 0x1000
	s_addc_u32 s97, s97, 0
	global_load_dwordx4 v[248:251], v128, s[96:97]
	s_add_u32 s96, s96, 0x1000
	s_addc_u32 s97, s97, 0
	global_load_dwordx4 v[252:255], v128, s[96:97]
	s_add_u32 s96, s96, 0x1000
	s_addc_u32 s97, s97, 0
	global_load_dwordx4 v[232:235], v128, s[96:97]
	s_add_u32 s96, s96, 0x1000
	s_addc_u32 s97, s97, 0
	global_load_dwordx4 v[154:157], v128, s[96:97]
	s_add_u32 s96, s96, 0x1000
	s_addc_u32 s97, s97, 0
	v_lshl_add_u64 v[146:147], v[146:147], 0, s[98:99]
	s_waitcnt vmcnt(40)
	v_lshl_add_u64 v[148:149], v[146:147], 0, s[100:101]
	v_mul_f32_e32 v158, v8, v137
	v_fma_f32 v166, -v209, v158, v166
	v_bfe_u32 v158, v166, 16, 1
	v_add3_u32 v166, v166, v158, s39
	global_store_short_d16_hi v[146:147], v166, off
	v_mul_f32_e32 v159, v9, v136
	v_fma_f32 v167, -v209, v159, v167
	v_bfe_u32 v159, v167, 16, 1
	v_add3_u32 v167, v167, v159, s39
	global_store_short_d16_hi v[146:147], v167, off offset:2048
	v_mul_f32_e32 v160, v10, v135
	v_fma_f32 v168, -v209, v160, v168
	v_bfe_u32 v160, v168, 16, 1
	v_add3_u32 v168, v168, v160, s39
	global_store_short_d16_hi v[148:149], v168, off
	v_mul_f32_e32 v150, v11, v134
	v_fma_f32 v169, -v209, v150, v169
	v_bfe_u32 v150, v169, 16, 1
	v_add3_u32 v169, v169, v150, s39
	global_store_short_d16_hi v[148:149], v169, off offset:2048
	v_mul_f32_e32 v158, v120, v137
	v_fma_f32 v170, -v209, v158, v170
	v_bfe_u32 v158, v170, 16, 1
	v_add3_u32 v170, v170, v158, s39
	global_store_short_d16_hi v[146:147], v170, off offset:64
	v_mul_f32_e32 v159, v121, v136
	v_fma_f32 v171, -v209, v159, v171
	v_bfe_u32 v159, v171, 16, 1
	v_add3_u32 v171, v171, v159, s39
	global_store_short_d16_hi v[146:147], v171, off offset:2112
	v_mul_f32_e32 v160, v122, v135
	v_fma_f32 v172, -v209, v160, v172
	v_bfe_u32 v160, v172, 16, 1
	v_add3_u32 v172, v172, v160, s39
	global_store_short_d16_hi v[148:149], v172, off offset:64
	v_mul_f32_e32 v150, v123, v134
	v_fma_f32 v173, -v209, v150, v173
	v_bfe_u32 v150, v173, 16, 1
	v_add3_u32 v173, v173, v150, s39
	global_store_short_d16_hi v[148:149], v173, off offset:2112
	v_mul_f32_e32 v158, v104, v137
	v_fma_f32 v174, -v209, v158, v174
	v_bfe_u32 v158, v174, 16, 1
	v_add3_u32 v174, v174, v158, s39
	global_store_short_d16_hi v[146:147], v174, off offset:128
	v_mul_f32_e32 v159, v105, v136
	v_fma_f32 v175, -v209, v159, v175
	v_bfe_u32 v159, v175, 16, 1
	v_add3_u32 v175, v175, v159, s39
	global_store_short_d16_hi v[146:147], v175, off offset:2176
	v_mul_f32_e32 v160, v106, v135
	v_fma_f32 v176, -v209, v160, v176
	v_bfe_u32 v160, v176, 16, 1
	v_add3_u32 v176, v176, v160, s39
	global_store_short_d16_hi v[148:149], v176, off offset:128
	v_mul_f32_e32 v150, v107, v134
	v_fma_f32 v177, -v209, v150, v177
	v_bfe_u32 v150, v177, 16, 1
	v_add3_u32 v177, v177, v150, s39
	global_store_short_d16_hi v[148:149], v177, off offset:2176
	v_mul_f32_e32 v158, v88, v137
	v_fma_f32 v178, -v209, v158, v178
	v_bfe_u32 v158, v178, 16, 1
	v_add3_u32 v178, v178, v158, s39
	global_store_short_d16_hi v[146:147], v178, off offset:192
	v_mul_f32_e32 v159, v89, v136
	v_fma_f32 v179, -v209, v159, v179
	v_bfe_u32 v159, v179, 16, 1
	v_add3_u32 v179, v179, v159, s39
	global_store_short_d16_hi v[146:147], v179, off offset:2240
	v_mul_f32_e32 v160, v90, v135
	v_fma_f32 v180, -v209, v160, v180
	v_bfe_u32 v160, v180, 16, 1
	v_add3_u32 v180, v180, v160, s39
	global_store_short_d16_hi v[148:149], v180, off offset:192
	v_mul_f32_e32 v150, v91, v134
	v_fma_f32 v181, -v209, v150, v181
	v_bfe_u32 v150, v181, 16, 1
	v_add3_u32 v181, v181, v150, s39
	global_store_short_d16_hi v[148:149], v181, off offset:2240
	v_mul_f32_e32 v158, v72, v137
	v_fma_f32 v182, -v209, v158, v182
	v_bfe_u32 v158, v182, 16, 1
	v_add3_u32 v182, v182, v158, s39
	global_store_short_d16_hi v[146:147], v182, off offset:256
	v_mul_f32_e32 v159, v73, v136
	v_fma_f32 v183, -v209, v159, v183
	v_bfe_u32 v159, v183, 16, 1
	v_add3_u32 v183, v183, v159, s39
	global_store_short_d16_hi v[146:147], v183, off offset:2304
	v_mul_f32_e32 v160, v74, v135
	v_fma_f32 v184, -v209, v160, v184
	v_bfe_u32 v160, v184, 16, 1
	v_add3_u32 v184, v184, v160, s39
	global_store_short_d16_hi v[148:149], v184, off offset:256
	v_mul_f32_e32 v150, v75, v134
	v_fma_f32 v185, -v209, v150, v185
	v_bfe_u32 v150, v185, 16, 1
	v_add3_u32 v185, v185, v150, s39
	global_store_short_d16_hi v[148:149], v185, off offset:2304
	v_mul_f32_e32 v158, v56, v137
	v_fma_f32 v186, -v209, v158, v186
	v_bfe_u32 v158, v186, 16, 1
	v_add3_u32 v186, v186, v158, s39
	global_store_short_d16_hi v[146:147], v186, off offset:320
	v_mul_f32_e32 v159, v57, v136
	v_fma_f32 v187, -v209, v159, v187
	v_bfe_u32 v159, v187, 16, 1
	v_add3_u32 v187, v187, v159, s39
	global_store_short_d16_hi v[146:147], v187, off offset:2368
	v_mul_f32_e32 v160, v58, v135
	v_fma_f32 v188, -v209, v160, v188
	v_bfe_u32 v160, v188, 16, 1
	v_add3_u32 v188, v188, v160, s39
	global_store_short_d16_hi v[148:149], v188, off offset:320
	v_mul_f32_e32 v150, v59, v134
	v_fma_f32 v189, -v209, v150, v189
	v_bfe_u32 v150, v189, 16, 1
	v_add3_u32 v189, v189, v150, s39
	global_store_short_d16_hi v[148:149], v189, off offset:2368
	v_mul_f32_e32 v158, v40, v137
	v_fma_f32 v190, -v209, v158, v190
	v_bfe_u32 v158, v190, 16, 1
	v_add3_u32 v190, v190, v158, s39
	global_store_short_d16_hi v[146:147], v190, off offset:384
	v_mul_f32_e32 v159, v41, v136
	v_fma_f32 v191, -v209, v159, v191
	v_bfe_u32 v159, v191, 16, 1
	v_add3_u32 v191, v191, v159, s39
	global_store_short_d16_hi v[146:147], v191, off offset:2432
	v_mul_f32_e32 v160, v42, v135
	v_fma_f32 v192, -v209, v160, v192
	v_bfe_u32 v160, v192, 16, 1
	v_add3_u32 v192, v192, v160, s39
	global_store_short_d16_hi v[148:149], v192, off offset:384
	v_mul_f32_e32 v150, v43, v134
	v_fma_f32 v193, -v209, v150, v193
	v_bfe_u32 v150, v193, 16, 1
	v_add3_u32 v193, v193, v150, s39
	global_store_short_d16_hi v[148:149], v193, off offset:2432
	v_mul_f32_e32 v158, v24, v137
	v_fma_f32 v194, -v209, v158, v194
	v_bfe_u32 v158, v194, 16, 1
	v_add3_u32 v194, v194, v158, s39
	global_store_short_d16_hi v[146:147], v194, off offset:448
	v_mul_f32_e32 v159, v25, v136
	v_fma_f32 v195, -v209, v159, v195
	v_bfe_u32 v159, v195, 16, 1
	v_add3_u32 v195, v195, v159, s39
	global_store_short_d16_hi v[146:147], v195, off offset:2496
	v_mul_f32_e32 v160, v26, v135
	v_fma_f32 v196, -v209, v160, v196
	v_bfe_u32 v160, v196, 16, 1
	v_add3_u32 v196, v196, v160, s39
	global_store_short_d16_hi v[148:149], v196, off offset:448
	v_mul_f32_e32 v150, v27, v134
	v_fma_f32 v197, -v209, v150, v197
	v_bfe_u32 v150, v197, 16, 1
	v_add3_u32 v197, v197, v150, s39
	global_store_short_d16_hi v[148:149], v197, off offset:2496
	v_lshl_add_u64 v[146:147], v[146:147], 0, s[98:99]
	s_waitcnt vmcnt(32)
	v_lshl_add_u64 v[148:149], v[146:147], 0, s[100:101]
	v_mul_f32_e32 v158, v12, v133
	v_fma_f32 v198, -v209, v158, v198
	v_bfe_u32 v158, v198, 16, 1
	v_add3_u32 v198, v198, v158, s39
	global_store_short_d16_hi v[146:147], v198, off
	v_mul_f32_e32 v159, v13, v132
	v_fma_f32 v199, -v209, v159, v199
	v_bfe_u32 v159, v199, 16, 1
	v_add3_u32 v199, v199, v159, s39
	global_store_short_d16_hi v[146:147], v199, off offset:2048
	v_mul_f32_e32 v160, v14, v131
	v_fma_f32 v200, -v209, v160, v200
	v_bfe_u32 v160, v200, 16, 1
	v_add3_u32 v200, v200, v160, s39
	global_store_short_d16_hi v[148:149], v200, off
	v_mul_f32_e32 v150, v15, v130
	v_fma_f32 v201, -v209, v150, v201
	v_bfe_u32 v150, v201, 16, 1
	v_add3_u32 v201, v201, v150, s39
	global_store_short_d16_hi v[148:149], v201, off offset:2048
	v_mul_f32_e32 v158, v124, v133
	v_fma_f32 v202, -v209, v158, v202
	v_bfe_u32 v158, v202, 16, 1
	v_add3_u32 v202, v202, v158, s39
	global_store_short_d16_hi v[146:147], v202, off offset:64
	v_mul_f32_e32 v159, v125, v132
	v_fma_f32 v203, -v209, v159, v203
	v_bfe_u32 v159, v203, 16, 1
	v_add3_u32 v203, v203, v159, s39
	global_store_short_d16_hi v[146:147], v203, off offset:2112
	v_mul_f32_e32 v160, v126, v131
	v_fma_f32 v204, -v209, v160, v204
	v_bfe_u32 v160, v204, 16, 1
	v_add3_u32 v204, v204, v160, s39
	global_store_short_d16_hi v[148:149], v204, off offset:64
	v_mul_f32_e32 v150, v127, v130
	v_fma_f32 v205, -v209, v150, v205
	v_bfe_u32 v150, v205, 16, 1
	v_add3_u32 v205, v205, v150, s39
	global_store_short_d16_hi v[148:149], v205, off offset:2112
	v_mul_f32_e32 v158, v108, v133
	v_fma_f32 v240, -v209, v158, v240
	v_bfe_u32 v158, v240, 16, 1
	v_add3_u32 v240, v240, v158, s39
	global_store_short_d16_hi v[146:147], v240, off offset:128
	v_mul_f32_e32 v159, v109, v132
	v_fma_f32 v241, -v209, v159, v241
	v_bfe_u32 v159, v241, 16, 1
	v_add3_u32 v241, v241, v159, s39
	global_store_short_d16_hi v[146:147], v241, off offset:2176
	v_mul_f32_e32 v160, v110, v131
	v_fma_f32 v242, -v209, v160, v242
	v_bfe_u32 v160, v242, 16, 1
	v_add3_u32 v242, v242, v160, s39
	global_store_short_d16_hi v[148:149], v242, off offset:128
	v_mul_f32_e32 v150, v111, v130
	v_fma_f32 v243, -v209, v150, v243
	v_bfe_u32 v150, v243, 16, 1
	v_add3_u32 v243, v243, v150, s39
	global_store_short_d16_hi v[148:149], v243, off offset:2176
	v_mul_f32_e32 v158, v92, v133
	v_fma_f32 v244, -v209, v158, v244
	v_bfe_u32 v158, v244, 16, 1
	v_add3_u32 v244, v244, v158, s39
	global_store_short_d16_hi v[146:147], v244, off offset:192
	v_mul_f32_e32 v159, v93, v132
	v_fma_f32 v245, -v209, v159, v245
	v_bfe_u32 v159, v245, 16, 1
	v_add3_u32 v245, v245, v159, s39
	global_store_short_d16_hi v[146:147], v245, off offset:2240
	v_mul_f32_e32 v160, v94, v131
	v_fma_f32 v246, -v209, v160, v246
	v_bfe_u32 v160, v246, 16, 1
	v_add3_u32 v246, v246, v160, s39
	global_store_short_d16_hi v[148:149], v246, off offset:192
	v_mul_f32_e32 v150, v95, v130
	v_fma_f32 v247, -v209, v150, v247
	v_bfe_u32 v150, v247, 16, 1
	v_add3_u32 v247, v247, v150, s39
	global_store_short_d16_hi v[148:149], v247, off offset:2240
	v_mul_f32_e32 v158, v76, v133
	v_fma_f32 v248, -v209, v158, v248
	v_bfe_u32 v158, v248, 16, 1
	v_add3_u32 v248, v248, v158, s39
	global_store_short_d16_hi v[146:147], v248, off offset:256
	v_mul_f32_e32 v159, v77, v132
	v_fma_f32 v249, -v209, v159, v249
	v_bfe_u32 v159, v249, 16, 1
	v_add3_u32 v249, v249, v159, s39
	global_store_short_d16_hi v[146:147], v249, off offset:2304
	v_mul_f32_e32 v160, v78, v131
	v_fma_f32 v250, -v209, v160, v250
	v_bfe_u32 v160, v250, 16, 1
	v_add3_u32 v250, v250, v160, s39
	global_store_short_d16_hi v[148:149], v250, off offset:256
	v_mul_f32_e32 v150, v79, v130
	v_fma_f32 v251, -v209, v150, v251
	v_bfe_u32 v150, v251, 16, 1
	v_add3_u32 v251, v251, v150, s39
	global_store_short_d16_hi v[148:149], v251, off offset:2304
	v_mul_f32_e32 v158, v60, v133
	v_fma_f32 v252, -v209, v158, v252
	v_bfe_u32 v158, v252, 16, 1
	v_add3_u32 v252, v252, v158, s39
	global_store_short_d16_hi v[146:147], v252, off offset:320
	v_mul_f32_e32 v159, v61, v132
	v_fma_f32 v253, -v209, v159, v253
	v_bfe_u32 v159, v253, 16, 1
	v_add3_u32 v253, v253, v159, s39
	global_store_short_d16_hi v[146:147], v253, off offset:2368
	v_mul_f32_e32 v160, v62, v131
	v_fma_f32 v254, -v209, v160, v254
	v_bfe_u32 v160, v254, 16, 1
	v_add3_u32 v254, v254, v160, s39
	global_store_short_d16_hi v[148:149], v254, off offset:320
	v_mul_f32_e32 v150, v63, v130
	v_fma_f32 v255, -v209, v150, v255
	v_bfe_u32 v150, v255, 16, 1
	v_add3_u32 v255, v255, v150, s39
	global_store_short_d16_hi v[148:149], v255, off offset:2368
	v_mul_f32_e32 v158, v44, v133
	v_fma_f32 v232, -v209, v158, v232
	v_bfe_u32 v158, v232, 16, 1
	v_add3_u32 v232, v232, v158, s39
	global_store_short_d16_hi v[146:147], v232, off offset:384
	v_mul_f32_e32 v159, v45, v132
	v_fma_f32 v233, -v209, v159, v233
	v_bfe_u32 v159, v233, 16, 1
	v_add3_u32 v233, v233, v159, s39
	global_store_short_d16_hi v[146:147], v233, off offset:2432
	v_mul_f32_e32 v160, v46, v131
	v_fma_f32 v234, -v209, v160, v234
	v_bfe_u32 v160, v234, 16, 1
	v_add3_u32 v234, v234, v160, s39
	global_store_short_d16_hi v[148:149], v234, off offset:384
	v_mul_f32_e32 v150, v47, v130
	v_fma_f32 v235, -v209, v150, v235
	v_bfe_u32 v150, v235, 16, 1
	v_add3_u32 v235, v235, v150, s39
	global_store_short_d16_hi v[148:149], v235, off offset:2432
	v_mul_f32_e32 v158, v28, v133
	v_fma_f32 v154, -v209, v158, v154
	v_bfe_u32 v158, v154, 16, 1
	v_add3_u32 v154, v154, v158, s39
	global_store_short_d16_hi v[146:147], v154, off offset:448
	v_mul_f32_e32 v159, v29, v132
	v_fma_f32 v155, -v209, v159, v155
	v_bfe_u32 v159, v155, 16, 1
	v_add3_u32 v155, v155, v159, s39
	global_store_short_d16_hi v[146:147], v155, off offset:2496
	v_mul_f32_e32 v160, v30, v131
	v_fma_f32 v156, -v209, v160, v156
	v_bfe_u32 v160, v156, 16, 1
	v_add3_u32 v156, v156, v160, s39
	global_store_short_d16_hi v[148:149], v156, off offset:448
	v_mul_f32_e32 v150, v31, v130
	v_fma_f32 v157, -v209, v150, v157
	v_bfe_u32 v150, v157, 16, 1
	v_add3_u32 v157, v157, v150, s39
	global_store_short_d16_hi v[148:149], v157, off offset:2496
	s_branch .LBB0_508

.LBB0_906:
	s_lshl_b32 s4, s80, 14
	v_add3_u32 v236, s4, v221, v220
	ds_read_b128 v[192:195], v236
	ds_read_b128 v[196:199], v236 offset:8192
	v_add3_u32 v236, s4, v222, v220
	ds_read_b128 v[200:203], v236
	ds_read_b128 v[204:207], v236 offset:8192
	v_add3_u32 v236, s4, v223, v220
	ds_read_b128 v[240:243], v236
	ds_read_b128 v[244:247], v236 offset:8192
	v_add3_u32 v236, s4, v225, v220
	ds_read_b128 v[248:251], v236
	ds_read_b128 v[252:255], v236 offset:8192
	s_waitcnt lgkmcnt(7)
	v_mfma_f32_32x32x16_bf16 v[144:159], v[192:195], v[160:163], 0
	s_waitcnt lgkmcnt(6)
	v_mfma_f32_32x32x16_bf16 v[128:143], v[196:199], v[160:163], 0
	v_add3_u32 v236, s4, v226, v220
	ds_read_b128 v[192:195], v236
	ds_read_b128 v[196:199], v236 offset:8192
	s_waitcnt lgkmcnt(7)
	v_mfma_f32_32x32x16_bf16 v[144:159], v[200:203], v[164:167], v[144:159]
	s_waitcnt lgkmcnt(6)
	v_mfma_f32_32x32x16_bf16 v[128:143], v[204:207], v[164:167], v[128:143]
	v_add3_u32 v236, s4, v227, v220
	ds_read_b128 v[200:203], v236
	ds_read_b128 v[204:207], v236 offset:8192
	s_waitcnt lgkmcnt(7)
	v_mfma_f32_32x32x16_bf16 v[144:159], v[240:243], v[168:171], v[144:159]
	s_waitcnt lgkmcnt(6)
	v_mfma_f32_32x32x16_bf16 v[128:143], v[244:247], v[168:171], v[128:143]
	v_add3_u32 v236, s4, v228, v220
	ds_read_b128 v[240:243], v236
	ds_read_b128 v[244:247], v236 offset:8192
	s_waitcnt lgkmcnt(7)
	v_mfma_f32_32x32x16_bf16 v[144:159], v[248:251], v[172:175], v[144:159]
	s_waitcnt lgkmcnt(6)
	v_mfma_f32_32x32x16_bf16 v[128:143], v[252:255], v[172:175], v[128:143]
	v_add3_u32 v236, s4, v229, v220
	ds_read_b128 v[248:251], v236
	ds_read_b128 v[252:255], v236 offset:8192
	s_waitcnt lgkmcnt(7)
	v_mfma_f32_32x32x16_bf16 v[144:159], v[192:195], v[176:179], v[144:159]
	s_waitcnt lgkmcnt(6)
	v_mfma_f32_32x32x16_bf16 v[128:143], v[196:199], v[176:179], v[128:143]
	s_waitcnt lgkmcnt(5)
	v_mfma_f32_32x32x16_bf16 v[144:159], v[200:203], v[180:183], v[144:159]
	s_waitcnt lgkmcnt(4)
	v_mfma_f32_32x32x16_bf16 v[128:143], v[204:207], v[180:183], v[128:143]
	s_waitcnt lgkmcnt(3)
	v_mfma_f32_32x32x16_bf16 v[144:159], v[240:243], v[184:187], v[144:159]
	s_waitcnt lgkmcnt(2)
	v_mfma_f32_32x32x16_bf16 v[128:143], v[244:247], v[184:187], v[128:143]
	s_waitcnt lgkmcnt(1)
	v_mfma_f32_32x32x16_bf16 v[144:159], v[248:251], v[188:191], v[144:159]
	s_waitcnt lgkmcnt(0)
	v_mfma_f32_32x32x16_bf16 v[128:143], v[252:255], v[188:191], v[128:143]
	v_max_f32_e32 v194, v231, v231
	s_nop 9
	v_max_f32_e32 v192, v144, v145
	v_max3_f32 v192, v192, v146, v147
	v_max3_f32 v192, v192, v148, v149
	v_max3_f32 v192, v192, v150, v151
	v_max3_f32 v192, v192, v152, v153
	v_max3_f32 v192, v192, v154, v155
	v_max3_f32 v192, v192, v156, v157
	v_max3_f32 v192, v192, v158, v159
	v_max3_f32 v192, v192, v128, v129
	v_max3_f32 v192, v192, v130, v131
	v_max3_f32 v192, v192, v132, v133
	v_max3_f32 v192, v192, v134, v135
	v_max3_f32 v192, v192, v136, v137
	v_max3_f32 v192, v192, v138, v139
	v_max3_f32 v192, v192, v140, v141
	v_max3_f32 v192, v192, v142, v143
	v_mov_b32_e32 v193, v192
	s_nop 1
	v_permlane32_swap_b32_e32 v192, v193
	v_max_f32_e32 v192, v192, v193
	v_max_f32_e32 v234, v194, v192
	v_sub_f32_e32 v193, v192, v231
	v_sub_f32_e32 v192, v231, v234
	v_mul_f32_e32 v192, 0x3e0293ee, v192
	v_exp_f32_e32 v192, v192
	v_cmp_ge_f32_e32 vcc, s42, v193
	s_cmp_eq_u64 vcc, exec
	s_cselect_b64 s[4:5], -1, 0
	v_cndmask_b32_e64 v233, v192, 1.0, s[4:5]
	v_cmp_gt_f32_e32 vcc, 1.0, v233
	s_cbranch_vccz .LBB0_910
	v_mov_b32_e32 v231, v234
	v_mul_f32_e32 v237, 0xbe0293ee, v234
	s_and_saveexec_b64 s[24:25], s[0:1]
	ds_write_b32 v224, v233 offset:128
	s_or_b64 exec, exec, s[24:25]
	s_waitcnt lgkmcnt(0)
	v_add_u32_e32 v192, s21, v210
	ds_read_b128 v[204:207], v192 offset:224
	ds_read_b128 v[200:203], v192 offset:192
	ds_read_b128 v[196:199], v192 offset:160
	ds_read_b128 v[192:195], v192 offset:128
	s_waitcnt lgkmcnt(3)
	v_pk_mul_f32 v[12:13], v[12:13], v[204:205]
	s_waitcnt lgkmcnt(2)
	v_pk_mul_f32 v[8:9], v[8:9], v[200:201]
	s_waitcnt lgkmcnt(1)
	v_pk_mul_f32 v[4:5], v[4:5], v[196:197]
	v_pk_mul_f32 v[14:15], v[14:15], v[206:207]
	v_pk_mul_f32 v[10:11], v[10:11], v[202:203]
	v_pk_mul_f32 v[6:7], v[6:7], v[198:199]
	s_waitcnt lgkmcnt(0)
	v_pk_mul_f32 v[2:3], v[2:3], v[194:195]
	v_pk_mul_f32 v[0:1], v[0:1], v[192:193]
	v_pk_mul_f32 v[124:125], v[124:125], v[204:205]
	v_pk_mul_f32 v[120:121], v[120:121], v[200:201]
	v_pk_mul_f32 v[116:117], v[116:117], v[196:197]
	v_pk_mul_f32 v[126:127], v[126:127], v[206:207]
	v_pk_mul_f32 v[122:123], v[122:123], v[202:203]
	v_pk_mul_f32 v[118:119], v[118:119], v[198:199]
	v_pk_mul_f32 v[114:115], v[114:115], v[194:195]
	v_pk_mul_f32 v[112:113], v[112:113], v[192:193]
	v_pk_mul_f32 v[108:109], v[108:109], v[204:205]
	v_pk_mul_f32 v[104:105], v[104:105], v[200:201]
	v_pk_mul_f32 v[100:101], v[100:101], v[196:197]
	v_pk_mul_f32 v[110:111], v[110:111], v[206:207]
	v_pk_mul_f32 v[106:107], v[106:107], v[202:203]
	v_pk_mul_f32 v[102:103], v[102:103], v[198:199]
	v_pk_mul_f32 v[98:99], v[98:99], v[194:195]
	v_pk_mul_f32 v[96:97], v[96:97], v[192:193]
	v_pk_mul_f32 v[92:93], v[92:93], v[204:205]
	v_pk_mul_f32 v[88:89], v[88:89], v[200:201]
	v_pk_mul_f32 v[84:85], v[84:85], v[196:197]
	v_pk_mul_f32 v[94:95], v[94:95], v[206:207]
	v_pk_mul_f32 v[90:91], v[90:91], v[202:203]
	v_pk_mul_f32 v[86:87], v[86:87], v[198:199]
	v_pk_mul_f32 v[82:83], v[82:83], v[194:195]
	v_pk_mul_f32 v[80:81], v[80:81], v[192:193]
	v_pk_mul_f32 v[76:77], v[76:77], v[204:205]
	v_pk_mul_f32 v[72:73], v[72:73], v[200:201]
	v_pk_mul_f32 v[68:69], v[68:69], v[196:197]
	v_pk_mul_f32 v[78:79], v[78:79], v[206:207]
	v_pk_mul_f32 v[74:75], v[74:75], v[202:203]
	v_pk_mul_f32 v[70:71], v[70:71], v[198:199]
	v_pk_mul_f32 v[66:67], v[66:67], v[194:195]
	v_pk_mul_f32 v[64:65], v[64:65], v[192:193]
	v_pk_mul_f32 v[60:61], v[60:61], v[204:205]
	v_pk_mul_f32 v[56:57], v[56:57], v[200:201]
	v_pk_mul_f32 v[52:53], v[52:53], v[196:197]
	v_pk_mul_f32 v[62:63], v[62:63], v[206:207]
	v_pk_mul_f32 v[58:59], v[58:59], v[202:203]
	v_pk_mul_f32 v[54:55], v[54:55], v[198:199]
	v_pk_mul_f32 v[50:51], v[50:51], v[194:195]
	v_pk_mul_f32 v[48:49], v[48:49], v[192:193]
	v_pk_mul_f32 v[44:45], v[44:45], v[204:205]
	v_pk_mul_f32 v[40:41], v[40:41], v[200:201]
	v_pk_mul_f32 v[36:37], v[36:37], v[196:197]
	v_pk_mul_f32 v[46:47], v[46:47], v[206:207]
	v_pk_mul_f32 v[42:43], v[42:43], v[202:203]
	v_pk_mul_f32 v[38:39], v[38:39], v[198:199]
	v_pk_mul_f32 v[34:35], v[34:35], v[194:195]
	v_pk_mul_f32 v[32:33], v[32:33], v[192:193]
	v_pk_mul_f32 v[28:29], v[28:29], v[204:205]
	v_pk_mul_f32 v[24:25], v[24:25], v[200:201]
	v_pk_mul_f32 v[20:21], v[20:21], v[196:197]
	v_pk_mul_f32 v[30:31], v[30:31], v[206:207]
	v_pk_mul_f32 v[26:27], v[26:27], v[202:203]
	v_pk_mul_f32 v[22:23], v[22:23], v[198:199]
	v_pk_mul_f32 v[18:19], v[18:19], v[194:195]
	v_pk_mul_f32 v[16:17], v[16:17], v[192:193]
.LBB0_910:
	v_fmamk_f32 v144, v144, 0x3e0293ee, v237
	v_fmamk_f32 v145, v145, 0x3e0293ee, v237
	v_fmamk_f32 v146, v146, 0x3e0293ee, v237
	v_fmamk_f32 v147, v147, 0x3e0293ee, v237
	v_fmamk_f32 v148, v148, 0x3e0293ee, v237
	v_fmamk_f32 v149, v149, 0x3e0293ee, v237
	v_fmamk_f32 v150, v150, 0x3e0293ee, v237
	v_fmamk_f32 v151, v151, 0x3e0293ee, v237
	v_fmamk_f32 v152, v152, 0x3e0293ee, v237
	v_fmamk_f32 v153, v153, 0x3e0293ee, v237
	v_fmamk_f32 v154, v154, 0x3e0293ee, v237
	v_fmamk_f32 v155, v155, 0x3e0293ee, v237
	v_fmamk_f32 v156, v156, 0x3e0293ee, v237
	v_fmamk_f32 v157, v157, 0x3e0293ee, v237
	v_fmamk_f32 v158, v158, 0x3e0293ee, v237
	v_fmamk_f32 v159, v159, 0x3e0293ee, v237
	v_fmamk_f32 v128, v128, 0x3e0293ee, v237
	v_fmamk_f32 v129, v129, 0x3e0293ee, v237
	v_fmamk_f32 v130, v130, 0x3e0293ee, v237
	v_fmamk_f32 v131, v131, 0x3e0293ee, v237
	v_fmamk_f32 v132, v132, 0x3e0293ee, v237
	v_fmamk_f32 v133, v133, 0x3e0293ee, v237
	v_fmamk_f32 v134, v134, 0x3e0293ee, v237
	v_fmamk_f32 v135, v135, 0x3e0293ee, v237
	v_fmamk_f32 v136, v136, 0x3e0293ee, v237
	v_fmamk_f32 v137, v137, 0x3e0293ee, v237
	v_fmamk_f32 v138, v138, 0x3e0293ee, v237
	v_fmamk_f32 v139, v139, 0x3e0293ee, v237
	v_fmamk_f32 v140, v140, 0x3e0293ee, v237
	v_fmamk_f32 v141, v141, 0x3e0293ee, v237
	v_fmamk_f32 v142, v142, 0x3e0293ee, v237
	v_fmamk_f32 v192, v143, 0x3e0293ee, v237
	v_exp_f32_e32 v143, v144
	v_exp_f32_e32 v145, v145
	v_exp_f32_e32 v146, v146
	v_exp_f32_e32 v147, v147
	v_exp_f32_e32 v148, v148
	v_exp_f32_e32 v193, v128
	v_exp_f32_e32 v149, v149
	v_add_f32_e32 v128, v145, v143
	v_exp_f32_e32 v150, v150
	v_add_f32_e32 v128, v146, v128
	v_exp_f32_e32 v151, v151
	v_add_f32_e32 v128, v147, v128
	v_exp_f32_e32 v152, v152
	v_add_f32_e32 v128, v148, v128
	v_exp_f32_e32 v153, v153
	v_add_f32_e32 v128, v149, v128
	v_exp_f32_e32 v154, v154
	v_add_f32_e32 v128, v150, v128
	v_exp_f32_e32 v155, v155
	v_add_f32_e32 v128, v151, v128
	v_exp_f32_e32 v156, v156
	v_add_f32_e32 v128, v152, v128
	v_exp_f32_e32 v157, v157
	v_add_f32_e32 v128, v153, v128
	v_exp_f32_e32 v158, v158
	v_add_f32_e32 v128, v154, v128
	v_exp_f32_e32 v159, v159
	v_add_f32_e32 v128, v155, v128
	v_add_f32_e32 v128, v156, v128
	v_exp_f32_e32 v194, v129
	v_add_f32_e32 v128, v157, v128
	v_exp_f32_e32 v195, v130
	v_add_f32_e32 v128, v158, v128
	v_exp_f32_e32 v196, v131
	v_add_f32_e32 v128, v159, v128
	v_exp_f32_e32 v197, v132
	v_add_f32_e32 v128, v193, v128
	v_exp_f32_e32 v198, v133
	v_add_f32_e32 v128, v194, v128
	v_exp_f32_e32 v199, v134
	v_add_f32_e32 v128, v195, v128
	v_exp_f32_e32 v135, v135
	v_add_f32_e32 v128, v196, v128
	v_exp_f32_e32 v200, v136
	v_add_f32_e32 v128, v197, v128
	v_exp_f32_e32 v201, v137
	v_add_f32_e32 v128, v198, v128
	v_exp_f32_e32 v202, v138
	v_add_f32_e32 v128, v199, v128
	v_exp_f32_e32 v203, v139
	v_add_f32_e32 v128, v135, v128
	v_exp_f32_e32 v204, v140
	v_add_f32_e32 v128, v200, v128
	v_exp_f32_e32 v205, v141
	v_add_f32_e32 v128, v201, v128
	v_exp_f32_e32 v206, v142
	v_add_f32_e32 v128, v202, v128
	v_exp_f32_e32 v192, v192
	v_add_f32_e32 v128, v203, v128
	v_add_f32_e32 v128, v204, v128
	v_add_f32_e32 v128, v205, v128
	v_add_f32_e32 v128, v206, v128
	v_add_f32_e32 v128, v192, v128
	v_fma_f32 v144, v232, v233, v128
	v_cvt_pk_bf16_f32 v128, v143, v145
	v_cvt_pk_bf16_f32 v129, v146, v147
	v_cvt_pk_bf16_f32 v130, v148, v149
	v_cvt_pk_bf16_f32 v131, v150, v151
	v_cvt_pk_bf16_f32 v136, v152, v153
	v_cvt_pk_bf16_f32 v137, v154, v155
	v_cvt_pk_bf16_f32 v138, v156, v157
	v_cvt_pk_bf16_f32 v139, v158, v159
	v_cvt_pk_bf16_f32 v132, v193, v194
	v_cvt_pk_bf16_f32 v133, v195, v196
	v_cvt_pk_bf16_f32 v134, v197, v198
	v_cvt_pk_bf16_f32 v135, v199, v135
	v_cvt_pk_bf16_f32 v140, v200, v201
	v_cvt_pk_bf16_f32 v141, v202, v203
	v_cvt_pk_bf16_f32 v142, v204, v205
	v_cvt_pk_bf16_f32 v143, v206, v192
	v_lshl_add_u32 v145, s80, 15, v230
	ds_read_b64_tr_b16 v[146:147], v145 offset:0
	ds_read_b64_tr_b16 v[148:149], v145 offset:4096
	ds_read_b64_tr_b16 v[150:151], v145 offset:512
	ds_read_b64_tr_b16 v[152:153], v145 offset:4608
	ds_read_b64_tr_b16 v[154:155], v145 offset:1024
	ds_read_b64_tr_b16 v[156:157], v145 offset:5120
	ds_read_b64_tr_b16 v[192:193], v145 offset:1536
	ds_read_b64_tr_b16 v[194:195], v145 offset:5632
	ds_read_b64_tr_b16 v[196:197], v145 offset:2048
	ds_read_b64_tr_b16 v[198:199], v145 offset:6144
	ds_read_b64_tr_b16 v[200:201], v145 offset:2560
	ds_read_b64_tr_b16 v[202:203], v145 offset:6656
	ds_read_b64_tr_b16 v[204:205], v145 offset:3072
	ds_read_b64_tr_b16 v[206:207], v145 offset:7168
	s_waitcnt lgkmcnt(12)
	s_nop 0
	v_mfma_f32_32x32x16_bf16 v[0:15], v[128:131], v[146:149], v[0:15]
	ds_read_b64_tr_b16 v[232:233], v145 offset:3584
	ds_read_b64_tr_b16 v[234:235], v145 offset:7680
	s_waitcnt lgkmcnt(12)
	v_mfma_f32_32x32x16_bf16 v[112:127], v[128:131], v[150:153], v[112:127]
	ds_read_b64_tr_b16 v[146:147], v145 offset:8192
	ds_read_b64_tr_b16 v[148:149], v145 offset:12288
	s_waitcnt lgkmcnt(12)
	v_mfma_f32_32x32x16_bf16 v[96:111], v[128:131], v[154:157], v[96:111]
	ds_read_b64_tr_b16 v[150:151], v145 offset:8704
	ds_read_b64_tr_b16 v[152:153], v145 offset:12800
	s_waitcnt lgkmcnt(12)
	v_mfma_f32_32x32x16_bf16 v[80:95], v[128:131], v[192:195], v[80:95]
	ds_read_b64_tr_b16 v[154:155], v145 offset:9216
	ds_read_b64_tr_b16 v[156:157], v145 offset:13312
	s_waitcnt lgkmcnt(12)
	v_mfma_f32_32x32x16_bf16 v[64:79], v[128:131], v[196:199], v[64:79]
	ds_read_b64_tr_b16 v[192:193], v145 offset:9728
	ds_read_b64_tr_b16 v[194:195], v145 offset:13824
	s_waitcnt lgkmcnt(12)
	v_mfma_f32_32x32x16_bf16 v[48:63], v[128:131], v[200:203], v[48:63]
	ds_read_b64_tr_b16 v[196:197], v145 offset:10240
	ds_read_b64_tr_b16 v[198:199], v145 offset:14336
	s_waitcnt lgkmcnt(12)
	v_mfma_f32_32x32x16_bf16 v[32:47], v[128:131], v[204:207], v[32:47]
	ds_read_b64_tr_b16 v[200:201], v145 offset:10752
	ds_read_b64_tr_b16 v[202:203], v145 offset:14848
	s_waitcnt lgkmcnt(12)
	v_mfma_f32_32x32x16_bf16 v[16:31], v[128:131], v[232:235], v[16:31]
	ds_read_b64_tr_b16 v[204:205], v145 offset:11264
	ds_read_b64_tr_b16 v[206:207], v145 offset:15360
	s_waitcnt lgkmcnt(12)
	v_mfma_f32_32x32x16_bf16 v[0:15], v[136:139], v[146:149], v[0:15]
	ds_read_b64_tr_b16 v[232:233], v145 offset:11776
	ds_read_b64_tr_b16 v[234:235], v145 offset:15872
	s_waitcnt lgkmcnt(12)
	v_mfma_f32_32x32x16_bf16 v[112:127], v[136:139], v[150:153], v[112:127]
	ds_read_b64_tr_b16 v[146:147], v145 offset:16384
	ds_read_b64_tr_b16 v[148:149], v145 offset:20480
	s_waitcnt lgkmcnt(12)
	v_mfma_f32_32x32x16_bf16 v[96:111], v[136:139], v[154:157], v[96:111]
	ds_read_b64_tr_b16 v[150:151], v145 offset:16896
	ds_read_b64_tr_b16 v[152:153], v145 offset:20992
	s_waitcnt lgkmcnt(12)
	v_mfma_f32_32x32x16_bf16 v[80:95], v[136:139], v[192:195], v[80:95]
	ds_read_b64_tr_b16 v[154:155], v145 offset:17408
	ds_read_b64_tr_b16 v[156:157], v145 offset:21504
	s_waitcnt lgkmcnt(12)
	v_mfma_f32_32x32x16_bf16 v[64:79], v[136:139], v[196:199], v[64:79]
	ds_read_b64_tr_b16 v[192:193], v145 offset:17920
	ds_read_b64_tr_b16 v[194:195], v145 offset:22016
	s_waitcnt lgkmcnt(12)
	v_mfma_f32_32x32x16_bf16 v[48:63], v[136:139], v[200:203], v[48:63]
	ds_read_b64_tr_b16 v[196:197], v145 offset:18432
	ds_read_b64_tr_b16 v[198:199], v145 offset:22528
	s_waitcnt lgkmcnt(12)
	v_mfma_f32_32x32x16_bf16 v[32:47], v[136:139], v[204:207], v[32:47]
	ds_read_b64_tr_b16 v[200:201], v145 offset:18944
	ds_read_b64_tr_b16 v[202:203], v145 offset:23040
	s_waitcnt lgkmcnt(12)
	v_mfma_f32_32x32x16_bf16 v[16:31], v[136:139], v[232:235], v[16:31]
	ds_read_b64_tr_b16 v[204:205], v145 offset:19456
	ds_read_b64_tr_b16 v[206:207], v145 offset:23552
	s_waitcnt lgkmcnt(12)
	v_mfma_f32_32x32x16_bf16 v[0:15], v[132:135], v[146:149], v[0:15]
	ds_read_b64_tr_b16 v[232:233], v145 offset:19968
	ds_read_b64_tr_b16 v[234:235], v145 offset:24064
	s_waitcnt lgkmcnt(12)
	v_mfma_f32_32x32x16_bf16 v[112:127], v[132:135], v[150:153], v[112:127]
	ds_read_b64_tr_b16 v[146:147], v145 offset:24576
	ds_read_b64_tr_b16 v[148:149], v145 offset:28672
	s_waitcnt lgkmcnt(12)
	v_mfma_f32_32x32x16_bf16 v[96:111], v[132:135], v[154:157], v[96:111]
	ds_read_b64_tr_b16 v[150:151], v145 offset:25088
	ds_read_b64_tr_b16 v[152:153], v145 offset:29184
	s_waitcnt lgkmcnt(12)
	v_mfma_f32_32x32x16_bf16 v[80:95], v[132:135], v[192:195], v[80:95]
	ds_read_b64_tr_b16 v[154:155], v145 offset:25600
	ds_read_b64_tr_b16 v[156:157], v145 offset:29696
	s_waitcnt lgkmcnt(12)
	v_mfma_f32_32x32x16_bf16 v[64:79], v[132:135], v[196:199], v[64:79]
	ds_read_b64_tr_b16 v[192:193], v145 offset:26112
	ds_read_b64_tr_b16 v[194:195], v145 offset:30208
	s_waitcnt lgkmcnt(12)
	v_mfma_f32_32x32x16_bf16 v[48:63], v[132:135], v[200:203], v[48:63]
	ds_read_b64_tr_b16 v[196:197], v145 offset:26624
	ds_read_b64_tr_b16 v[198:199], v145 offset:30720
	s_waitcnt lgkmcnt(12)
	v_mfma_f32_32x32x16_bf16 v[32:47], v[132:135], v[204:207], v[32:47]
	ds_read_b64_tr_b16 v[200:201], v145 offset:27136
	ds_read_b64_tr_b16 v[202:203], v145 offset:31232
	s_waitcnt lgkmcnt(12)
	v_mfma_f32_32x32x16_bf16 v[16:31], v[132:135], v[232:235], v[16:31]
	ds_read_b64_tr_b16 v[204:205], v145 offset:27648
	ds_read_b64_tr_b16 v[206:207], v145 offset:31744
	s_waitcnt lgkmcnt(12)
	v_mfma_f32_32x32x16_bf16 v[0:15], v[140:143], v[146:149], v[0:15]
	ds_read_b64_tr_b16 v[232:233], v145 offset:28160
	ds_read_b64_tr_b16 v[234:235], v145 offset:32256
	s_waitcnt lgkmcnt(12)
	v_mfma_f32_32x32x16_bf16 v[112:127], v[140:143], v[150:153], v[112:127]
	s_waitcnt lgkmcnt(10)
	v_mfma_f32_32x32x16_bf16 v[96:111], v[140:143], v[154:157], v[96:111]
	s_waitcnt lgkmcnt(8)
	v_mfma_f32_32x32x16_bf16 v[80:95], v[140:143], v[192:195], v[80:95]
	s_waitcnt lgkmcnt(6)
	v_mfma_f32_32x32x16_bf16 v[64:79], v[140:143], v[196:199], v[64:79]
	s_add_i32 s4, s80, 1
	s_cmp_lg_u32 s80, 2
	s_cselect_b32 s80, s4, 0
	s_add_i32 s4, s78, 1
	s_cmp_lg_u32 s78, 2
	s_cselect_b32 s78, s4, 0
	s_add_u32 s22, s22, 0x20000
	s_waitcnt lgkmcnt(4)
	v_mfma_f32_32x32x16_bf16 v[48:63], v[140:143], v[200:203], v[48:63]
	s_addc_u32 s23, s23, 0
	s_add_i32 s86, s86, 1
	s_cmp_eq_u32 s22, 0x800000
	s_waitcnt lgkmcnt(2)
	v_mfma_f32_32x32x16_bf16 v[32:47], v[140:143], v[204:207], v[32:47]
	s_waitcnt lgkmcnt(0)
	v_mfma_f32_32x32x16_bf16 v[16:31], v[140:143], v[232:235], v[16:31]
	s_cbranch_scc1 .LBB0_914
	v_mov_b32_e32 v232, v144
	s_cmp_eq_u32 s22, 0x7e0000
	s_mov_b64 s[4:5], -1
	s_cbranch_scc1 .LBB0_903

.LBB0_914:
	v_mov_b32_e32 v129, v144
	s_nop 1
	v_permlane32_swap_b32_e32 v144, v129
	v_add_f32_e32 v144, v144, v129
	s_and_saveexec_b64 s[4:5], s[0:1]
	ds_write_b32 v224, v144
	s_or_b64 exec, exec, s[4:5]
	s_waitcnt lgkmcnt(0)
	v_add_u32_e32 v136, s21, v210
	ds_read_b128 v[128:131], v136
	ds_read_b128 v[132:135], v136 offset:32
	s_ashr_i32 s21, s20, 31
	s_lshl_b64 s[0:1], s[20:21], 12
	ds_read_b128 v[138:141], v136 offset:96
	s_waitcnt lgkmcnt(2)
	v_rcp_f32_e32 v142, v128
	v_rcp_f32_e32 v145, v129
	v_rcp_f32_e32 v152, v130
	v_rcp_f32_e32 v161, v131
	ds_read_b128 v[128:131], v136 offset:64
	s_waitcnt lgkmcnt(2)
	v_rcp_f32_e32 v162, v132
	v_rcp_f32_e32 v163, v133
	v_rcp_f32_e32 v164, v134
	v_rcp_f32_e32 v165, v135
	s_waitcnt lgkmcnt(0)
	v_rcp_f32_e32 v137, v128
	v_rcp_f32_e32 v136, v129
	v_rcp_f32_e32 v135, v130
	v_rcp_f32_e32 v134, v131
	v_rcp_f32_e32 v133, v138
	v_rcp_f32_e32 v132, v139
	v_rcp_f32_e32 v131, v140
	v_rcp_f32_e32 v130, v141
	s_add_u32 s0, s66, s0
	s_addc_u32 s1, s67, s1
	s_mov_b64 s[4:5], -1
	s_andn2_b64 vcc, exec, s[18:19]
	v_lshlrev_b32_e32 v210, 2, v219
	v_lshlrev_b32_e32 v128, 14, v218
	v_lshl_add_u32 v129, v218, 5, v219
	v_lshlrev_b32_e32 v128, 4, v129
	s_mov_b32 s96, s0
	s_mov_b32 s97, s1
	s_cbranch_vccnz .Lepi1_p0
	s_lshl_b64 s[4:5], s[20:21], 11
	s_add_u32 s4, s68, s4
	s_addc_u32 s5, s69, s5
	v_lshlrev_b32_e32 v140, 1, v219
	v_lshl_add_u32 v140, v218, 13, v140
	v_mov_b32_e32 v141, 0
	v_lshl_add_u64 v[146:147], s[4:5], 0, v[140:141]
	s_mov_b64 s[100:101], 0x1000
	s_mov_b64 s[98:99], 0x4000
	global_load_dwordx4 v[166:169], v128, s[96:97]
	s_add_u32 s96, s96, 0x1000
	s_addc_u32 s97, s97, 0
	global_load_dwordx4 v[170:173], v128, s[96:97]
	s_add_u32 s96, s96, 0x1000
	s_addc_u32 s97, s97, 0
	global_load_dwordx4 v[174:177], v128, s[96:97]
	s_add_u32 s96, s96, 0x1000
	s_addc_u32 s97, s97, 0
	global_load_dwordx4 v[178:181], v128, s[96:97]
	s_add_u32 s96, s96, 0x1000
	s_addc_u32 s97, s97, 0
	global_load_dwordx4 v[182:185], v128, s[96:97]
	s_add_u32 s96, s96, 0x1000
	s_addc_u32 s97, s97, 0
	global_load_dwordx4 v[186:189], v128, s[96:97]
	s_add_u32 s96, s96, 0x1000
	s_addc_u32 s97, s97, 0
	global_load_dwordx4 v[190:193], v128, s[96:97]
	s_add_u32 s96, s96, 0x1000
	s_addc_u32 s97, s97, 0
	global_load_dwordx4 v[194:197], v128, s[96:97]
	s_add_u32 s96, s96, 0x1000
	s_addc_u32 s97, s97, 0
	global_load_dwordx4 v[198:201], v128, s[96:97]
	s_add_u32 s96, s96, 0x1000
	s_addc_u32 s97, s97, 0
	global_load_dwordx4 v[202:205], v128, s[96:97]
	s_add_u32 s96, s96, 0x1000
	s_addc_u32 s97, s97, 0
	global_load_dwordx4 v[240:243], v128, s[96:97]
	s_add_u32 s96, s96, 0x1000
	s_addc_u32 s97, s97, 0
	global_load_dwordx4 v[244:247], v128, s[96:97]
	s_add_u32 s96, s96, 0x1000
	s_addc_u32 s97, s97, 0
	global_load_dwordx4 v[248:251], v128, s[96:97]
	s_add_u32 s96, s96, 0x1000
	s_addc_u32 s97, s97, 0
	global_load_dwordx4 v[252:255], v128, s[96:97]
	s_add_u32 s96, s96, 0x1000
	s_addc_u32 s97, s97, 0
	global_load_dwordx4 v[232:235], v128, s[96:97]
	s_add_u32 s96, s96, 0x1000
	s_addc_u32 s97, s97, 0
	global_load_dwordx4 v[154:157], v128, s[96:97]
	s_add_u32 s96, s96, 0x1000
	s_addc_u32 s97, s97, 0
	s_waitcnt vmcnt(8)
	v_lshl_add_u64 v[148:149], v[146:147], 0, s[100:101]
	v_mul_f32_e32 v158, v0, v142
	v_fma_f32 v166, -v209, v158, v166
	v_bfe_u32 v158, v166, 16, 1
	v_add3_u32 v166, v166, v158, s43
	global_store_short_d16_hi v[146:147], v166, off
	v_mul_f32_e32 v159, v1, v145
	v_fma_f32 v167, -v209, v159, v167
	v_bfe_u32 v159, v167, 16, 1
	v_add3_u32 v167, v167, v159, s43
	global_store_short_d16_hi v[146:147], v167, off offset:2048
	v_mul_f32_e32 v160, v2, v152
	v_fma_f32 v168, -v209, v160, v168
	v_bfe_u32 v160, v168, 16, 1
	v_add3_u32 v168, v168, v160, s43
	global_store_short_d16_hi v[148:149], v168, off
	v_mul_f32_e32 v150, v3, v161
	v_fma_f32 v169, -v209, v150, v169
	v_bfe_u32 v150, v169, 16, 1
	v_add3_u32 v169, v169, v150, s43
	global_store_short_d16_hi v[148:149], v169, off offset:2048
	v_mul_f32_e32 v158, v112, v142
	v_fma_f32 v170, -v209, v158, v170
	v_bfe_u32 v158, v170, 16, 1
	v_add3_u32 v170, v170, v158, s43
	global_store_short_d16_hi v[146:147], v170, off offset:64
	v_mul_f32_e32 v159, v113, v145
	v_fma_f32 v171, -v209, v159, v171
	v_bfe_u32 v159, v171, 16, 1
	v_add3_u32 v171, v171, v159, s43
	global_store_short_d16_hi v[146:147], v171, off offset:2112
	v_mul_f32_e32 v160, v114, v152
	v_fma_f32 v172, -v209, v160, v172
	v_bfe_u32 v160, v172, 16, 1
	v_add3_u32 v172, v172, v160, s43
	global_store_short_d16_hi v[148:149], v172, off offset:64
	v_mul_f32_e32 v150, v115, v161
	v_fma_f32 v173, -v209, v150, v173
	v_bfe_u32 v150, v173, 16, 1
	v_add3_u32 v173, v173, v150, s43
	global_store_short_d16_hi v[148:149], v173, off offset:2112
	v_mul_f32_e32 v158, v96, v142
	v_fma_f32 v174, -v209, v158, v174
	v_bfe_u32 v158, v174, 16, 1
	v_add3_u32 v174, v174, v158, s43
	global_store_short_d16_hi v[146:147], v174, off offset:128
	v_mul_f32_e32 v159, v97, v145
	v_fma_f32 v175, -v209, v159, v175
	v_bfe_u32 v159, v175, 16, 1
	v_add3_u32 v175, v175, v159, s43
	global_store_short_d16_hi v[146:147], v175, off offset:2176
	v_mul_f32_e32 v160, v98, v152
	v_fma_f32 v176, -v209, v160, v176
	v_bfe_u32 v160, v176, 16, 1
	v_add3_u32 v176, v176, v160, s43
	global_store_short_d16_hi v[148:149], v176, off offset:128
	v_mul_f32_e32 v150, v99, v161
	v_fma_f32 v177, -v209, v150, v177
	v_bfe_u32 v150, v177, 16, 1
	v_add3_u32 v177, v177, v150, s43
	global_store_short_d16_hi v[148:149], v177, off offset:2176
	v_mul_f32_e32 v158, v80, v142
	v_fma_f32 v178, -v209, v158, v178
	v_bfe_u32 v158, v178, 16, 1
	v_add3_u32 v178, v178, v158, s43
	global_store_short_d16_hi v[146:147], v178, off offset:192
	v_mul_f32_e32 v159, v81, v145
	v_fma_f32 v179, -v209, v159, v179
	v_bfe_u32 v159, v179, 16, 1
	v_add3_u32 v179, v179, v159, s43
	global_store_short_d16_hi v[146:147], v179, off offset:2240
	v_mul_f32_e32 v160, v82, v152
	v_fma_f32 v180, -v209, v160, v180
	v_bfe_u32 v160, v180, 16, 1
	v_add3_u32 v180, v180, v160, s43
	global_store_short_d16_hi v[148:149], v180, off offset:192
	v_mul_f32_e32 v150, v83, v161
	v_fma_f32 v181, -v209, v150, v181
	v_bfe_u32 v150, v181, 16, 1
	v_add3_u32 v181, v181, v150, s43
	global_store_short_d16_hi v[148:149], v181, off offset:2240
	v_mul_f32_e32 v158, v64, v142
	v_fma_f32 v182, -v209, v158, v182
	v_bfe_u32 v158, v182, 16, 1
	v_add3_u32 v182, v182, v158, s43
	global_store_short_d16_hi v[146:147], v182, off offset:256
	v_mul_f32_e32 v159, v65, v145
	v_fma_f32 v183, -v209, v159, v183
	v_bfe_u32 v159, v183, 16, 1
	v_add3_u32 v183, v183, v159, s43
	global_store_short_d16_hi v[146:147], v183, off offset:2304
	v_mul_f32_e32 v160, v66, v152
	v_fma_f32 v184, -v209, v160, v184
	v_bfe_u32 v160, v184, 16, 1
	v_add3_u32 v184, v184, v160, s43
	global_store_short_d16_hi v[148:149], v184, off offset:256
	v_mul_f32_e32 v150, v67, v161
	v_fma_f32 v185, -v209, v150, v185
	v_bfe_u32 v150, v185, 16, 1
	v_add3_u32 v185, v185, v150, s43
	global_store_short_d16_hi v[148:149], v185, off offset:2304
	v_mul_f32_e32 v158, v48, v142
	v_fma_f32 v186, -v209, v158, v186
	v_bfe_u32 v158, v186, 16, 1
	v_add3_u32 v186, v186, v158, s43
	global_store_short_d16_hi v[146:147], v186, off offset:320
	v_mul_f32_e32 v159, v49, v145
	v_fma_f32 v187, -v209, v159, v187
	v_bfe_u32 v159, v187, 16, 1
	v_add3_u32 v187, v187, v159, s43
	global_store_short_d16_hi v[146:147], v187, off offset:2368
	v_mul_f32_e32 v160, v50, v152
	v_fma_f32 v188, -v209, v160, v188
	v_bfe_u32 v160, v188, 16, 1
	v_add3_u32 v188, v188, v160, s43
	global_store_short_d16_hi v[148:149], v188, off offset:320
	v_mul_f32_e32 v150, v51, v161
	v_fma_f32 v189, -v209, v150, v189
	v_bfe_u32 v150, v189, 16, 1
	v_add3_u32 v189, v189, v150, s43
	global_store_short_d16_hi v[148:149], v189, off offset:2368
	v_mul_f32_e32 v158, v32, v142
	v_fma_f32 v190, -v209, v158, v190
	v_bfe_u32 v158, v190, 16, 1
	v_add3_u32 v190, v190, v158, s43
	global_store_short_d16_hi v[146:147], v190, off offset:384
	v_mul_f32_e32 v159, v33, v145
	v_fma_f32 v191, -v209, v159, v191
	v_bfe_u32 v159, v191, 16, 1
	v_add3_u32 v191, v191, v159, s43
	global_store_short_d16_hi v[146:147], v191, off offset:2432
	v_mul_f32_e32 v160, v34, v152
	v_fma_f32 v192, -v209, v160, v192
	v_bfe_u32 v160, v192, 16, 1
	v_add3_u32 v192, v192, v160, s43
	global_store_short_d16_hi v[148:149], v192, off offset:384
	v_mul_f32_e32 v150, v35, v161
	v_fma_f32 v193, -v209, v150, v193
	v_bfe_u32 v150, v193, 16, 1
	v_add3_u32 v193, v193, v150, s43
	global_store_short_d16_hi v[148:149], v193, off offset:2432
	v_mul_f32_e32 v158, v16, v142
	v_fma_f32 v194, -v209, v158, v194
	v_bfe_u32 v158, v194, 16, 1
	v_add3_u32 v194, v194, v158, s43
	global_store_short_d16_hi v[146:147], v194, off offset:448
	v_mul_f32_e32 v159, v17, v145
	v_fma_f32 v195, -v209, v159, v195
	v_bfe_u32 v159, v195, 16, 1
	v_add3_u32 v195, v195, v159, s43
	global_store_short_d16_hi v[146:147], v195, off offset:2496
	v_mul_f32_e32 v160, v18, v152
	v_fma_f32 v196, -v209, v160, v196
	v_bfe_u32 v160, v196, 16, 1
	v_add3_u32 v196, v196, v160, s43
	global_store_short_d16_hi v[148:149], v196, off offset:448
	v_mul_f32_e32 v150, v19, v161
	v_fma_f32 v197, -v209, v150, v197
	v_bfe_u32 v150, v197, 16, 1
	v_add3_u32 v197, v197, v150, s43
	global_store_short_d16_hi v[148:149], v197, off offset:2496
	global_load_dwordx4 v[166:169], v128, s[96:97]
	s_add_u32 s96, s96, 0x1000
	s_addc_u32 s97, s97, 0
	global_load_dwordx4 v[170:173], v128, s[96:97]
	s_add_u32 s96, s96, 0x1000
	s_addc_u32 s97, s97, 0
	global_load_dwordx4 v[174:177], v128, s[96:97]
	s_add_u32 s96, s96, 0x1000
	s_addc_u32 s97, s97, 0
	global_load_dwordx4 v[178:181], v128, s[96:97]
	s_add_u32 s96, s96, 0x1000
	s_addc_u32 s97, s97, 0
	global_load_dwordx4 v[182:185], v128, s[96:97]
	s_add_u32 s96, s96, 0x1000
	s_addc_u32 s97, s97, 0
	global_load_dwordx4 v[186:189], v128, s[96:97]
	s_add_u32 s96, s96, 0x1000
	s_addc_u32 s97, s97, 0
	global_load_dwordx4 v[190:193], v128, s[96:97]
	s_add_u32 s96, s96, 0x1000
	s_addc_u32 s97, s97, 0
	global_load_dwordx4 v[194:197], v128, s[96:97]
	s_add_u32 s96, s96, 0x1000
	s_addc_u32 s97, s97, 0
	v_lshl_add_u64 v[146:147], v[146:147], 0, s[98:99]
	s_waitcnt vmcnt(40)
	v_lshl_add_u64 v[148:149], v[146:147], 0, s[100:101]
	v_mul_f32_e32 v158, v4, v162
	v_fma_f32 v198, -v209, v158, v198
	v_bfe_u32 v158, v198, 16, 1
	v_add3_u32 v198, v198, v158, s43
	global_store_short_d16_hi v[146:147], v198, off
	v_mul_f32_e32 v159, v5, v163
	v_fma_f32 v199, -v209, v159, v199
	v_bfe_u32 v159, v199, 16, 1
	v_add3_u32 v199, v199, v159, s43
	global_store_short_d16_hi v[146:147], v199, off offset:2048
	v_mul_f32_e32 v160, v6, v164
	v_fma_f32 v200, -v209, v160, v200
	v_bfe_u32 v160, v200, 16, 1
	v_add3_u32 v200, v200, v160, s43
	global_store_short_d16_hi v[148:149], v200, off
	v_mul_f32_e32 v150, v7, v165
	v_fma_f32 v201, -v209, v150, v201
	v_bfe_u32 v150, v201, 16, 1
	v_add3_u32 v201, v201, v150, s43
	global_store_short_d16_hi v[148:149], v201, off offset:2048
	v_mul_f32_e32 v158, v116, v162
	v_fma_f32 v202, -v209, v158, v202
	v_bfe_u32 v158, v202, 16, 1
	v_add3_u32 v202, v202, v158, s43
	global_store_short_d16_hi v[146:147], v202, off offset:64
	v_mul_f32_e32 v159, v117, v163
	v_fma_f32 v203, -v209, v159, v203
	v_bfe_u32 v159, v203, 16, 1
	v_add3_u32 v203, v203, v159, s43
	global_store_short_d16_hi v[146:147], v203, off offset:2112
	v_mul_f32_e32 v160, v118, v164
	v_fma_f32 v204, -v209, v160, v204
	v_bfe_u32 v160, v204, 16, 1
	v_add3_u32 v204, v204, v160, s43
	global_store_short_d16_hi v[148:149], v204, off offset:64
	v_mul_f32_e32 v150, v119, v165
	v_fma_f32 v205, -v209, v150, v205
	v_bfe_u32 v150, v205, 16, 1
	v_add3_u32 v205, v205, v150, s43
	global_store_short_d16_hi v[148:149], v205, off offset:2112
	v_mul_f32_e32 v158, v100, v162
	v_fma_f32 v240, -v209, v158, v240
	v_bfe_u32 v158, v240, 16, 1
	v_add3_u32 v240, v240, v158, s43
	global_store_short_d16_hi v[146:147], v240, off offset:128
	v_mul_f32_e32 v159, v101, v163
	v_fma_f32 v241, -v209, v159, v241
	v_bfe_u32 v159, v241, 16, 1
	v_add3_u32 v241, v241, v159, s43
	global_store_short_d16_hi v[146:147], v241, off offset:2176
	v_mul_f32_e32 v160, v102, v164
	v_fma_f32 v242, -v209, v160, v242
	v_bfe_u32 v160, v242, 16, 1
	v_add3_u32 v242, v242, v160, s43
	global_store_short_d16_hi v[148:149], v242, off offset:128
	v_mul_f32_e32 v150, v103, v165
	v_fma_f32 v243, -v209, v150, v243
	v_bfe_u32 v150, v243, 16, 1
	v_add3_u32 v243, v243, v150, s43
	global_store_short_d16_hi v[148:149], v243, off offset:2176
	v_mul_f32_e32 v158, v84, v162
	v_fma_f32 v244, -v209, v158, v244
	v_bfe_u32 v158, v244, 16, 1
	v_add3_u32 v244, v244, v158, s43
	global_store_short_d16_hi v[146:147], v244, off offset:192
	v_mul_f32_e32 v159, v85, v163
	v_fma_f32 v245, -v209, v159, v245
	v_bfe_u32 v159, v245, 16, 1
	v_add3_u32 v245, v245, v159, s43
	global_store_short_d16_hi v[146:147], v245, off offset:2240
	v_mul_f32_e32 v160, v86, v164
	v_fma_f32 v246, -v209, v160, v246
	v_bfe_u32 v160, v246, 16, 1
	v_add3_u32 v246, v246, v160, s43
	global_store_short_d16_hi v[148:149], v246, off offset:192
	v_mul_f32_e32 v150, v87, v165
	v_fma_f32 v247, -v209, v150, v247
	v_bfe_u32 v150, v247, 16, 1
	v_add3_u32 v247, v247, v150, s43
	global_store_short_d16_hi v[148:149], v247, off offset:2240
	v_mul_f32_e32 v158, v68, v162
	v_fma_f32 v248, -v209, v158, v248
	v_bfe_u32 v158, v248, 16, 1
	v_add3_u32 v248, v248, v158, s43
	global_store_short_d16_hi v[146:147], v248, off offset:256
	v_mul_f32_e32 v159, v69, v163
	v_fma_f32 v249, -v209, v159, v249
	v_bfe_u32 v159, v249, 16, 1
	v_add3_u32 v249, v249, v159, s43
	global_store_short_d16_hi v[146:147], v249, off offset:2304
	v_mul_f32_e32 v160, v70, v164
	v_fma_f32 v250, -v209, v160, v250
	v_bfe_u32 v160, v250, 16, 1
	v_add3_u32 v250, v250, v160, s43
	global_store_short_d16_hi v[148:149], v250, off offset:256
	v_mul_f32_e32 v150, v71, v165
	v_fma_f32 v251, -v209, v150, v251
	v_bfe_u32 v150, v251, 16, 1
	v_add3_u32 v251, v251, v150, s43
	global_store_short_d16_hi v[148:149], v251, off offset:2304
	v_mul_f32_e32 v158, v52, v162
	v_fma_f32 v252, -v209, v158, v252
	v_bfe_u32 v158, v252, 16, 1
	v_add3_u32 v252, v252, v158, s43
	global_store_short_d16_hi v[146:147], v252, off offset:320
	v_mul_f32_e32 v159, v53, v163
	v_fma_f32 v253, -v209, v159, v253
	v_bfe_u32 v159, v253, 16, 1
	v_add3_u32 v253, v253, v159, s43
	global_store_short_d16_hi v[146:147], v253, off offset:2368
	v_mul_f32_e32 v160, v54, v164
	v_fma_f32 v254, -v209, v160, v254
	v_bfe_u32 v160, v254, 16, 1
	v_add3_u32 v254, v254, v160, s43
	global_store_short_d16_hi v[148:149], v254, off offset:320
	v_mul_f32_e32 v150, v55, v165
	v_fma_f32 v255, -v209, v150, v255
	v_bfe_u32 v150, v255, 16, 1
	v_add3_u32 v255, v255, v150, s43
	global_store_short_d16_hi v[148:149], v255, off offset:2368
	v_mul_f32_e32 v158, v36, v162
	v_fma_f32 v232, -v209, v158, v232
	v_bfe_u32 v158, v232, 16, 1
	v_add3_u32 v232, v232, v158, s43
	global_store_short_d16_hi v[146:147], v232, off offset:384
	v_mul_f32_e32 v159, v37, v163
	v_fma_f32 v233, -v209, v159, v233
	v_bfe_u32 v159, v233, 16, 1
	v_add3_u32 v233, v233, v159, s43
	global_store_short_d16_hi v[146:147], v233, off offset:2432
	v_mul_f32_e32 v160, v38, v164
	v_fma_f32 v234, -v209, v160, v234
	v_bfe_u32 v160, v234, 16, 1
	v_add3_u32 v234, v234, v160, s43
	global_store_short_d16_hi v[148:149], v234, off offset:384
	v_mul_f32_e32 v150, v39, v165
	v_fma_f32 v235, -v209, v150, v235
	v_bfe_u32 v150, v235, 16, 1
	v_add3_u32 v235, v235, v150, s43
	global_store_short_d16_hi v[148:149], v235, off offset:2432
	v_mul_f32_e32 v158, v20, v162
	v_fma_f32 v154, -v209, v158, v154
	v_bfe_u32 v158, v154, 16, 1
	v_add3_u32 v154, v154, v158, s43
	global_store_short_d16_hi v[146:147], v154, off offset:448
	v_mul_f32_e32 v159, v21, v163
	v_fma_f32 v155, -v209, v159, v155
	v_bfe_u32 v159, v155, 16, 1
	v_add3_u32 v155, v155, v159, s43
	global_store_short_d16_hi v[146:147], v155, off offset:2496
	v_mul_f32_e32 v160, v22, v164
	v_fma_f32 v156, -v209, v160, v156
	v_bfe_u32 v160, v156, 16, 1
	v_add3_u32 v156, v156, v160, s43
	global_store_short_d16_hi v[148:149], v156, off offset:448
	v_mul_f32_e32 v150, v23, v165
	v_fma_f32 v157, -v209, v150, v157
	v_bfe_u32 v150, v157, 16, 1
	v_add3_u32 v157, v157, v150, s43
	global_store_short_d16_hi v[148:149], v157, off offset:2496
	global_load_dwordx4 v[198:201], v128, s[96:97]
	s_add_u32 s96, s96, 0x1000
	s_addc_u32 s97, s97, 0
	global_load_dwordx4 v[202:205], v128, s[96:97]
	s_add_u32 s96, s96, 0x1000
	s_addc_u32 s97, s97, 0
	global_load_dwordx4 v[240:243], v128, s[96:97]
	s_add_u32 s96, s96, 0x1000
	s_addc_u32 s97, s97, 0
	global_load_dwordx4 v[244:247], v128, s[96:97]
	s_add_u32 s96, s96, 0x1000
	s_addc_u32 s97, s97, 0
	global_load_dwordx4 v[248:251], v128, s[96:97]
	s_add_u32 s96, s96, 0x1000
	s_addc_u32 s97, s97, 0
	global_load_dwordx4 v[252:255], v128, s[96:97]
	s_add_u32 s96, s96, 0x1000
	s_addc_u32 s97, s97, 0
	global_load_dwordx4 v[232:235], v128, s[96:97]
	s_add_u32 s96, s96, 0x1000
	s_addc_u32 s97, s97, 0
	global_load_dwordx4 v[154:157], v128, s[96:97]
	s_add_u32 s96, s96, 0x1000
	s_addc_u32 s97, s97, 0
	v_lshl_add_u64 v[146:147], v[146:147], 0, s[98:99]
	s_waitcnt vmcnt(40)
	v_lshl_add_u64 v[148:149], v[146:147], 0, s[100:101]
	v_mul_f32_e32 v158, v8, v137
	v_fma_f32 v166, -v209, v158, v166
	v_bfe_u32 v158, v166, 16, 1
	v_add3_u32 v166, v166, v158, s43
	global_store_short_d16_hi v[146:147], v166, off
	v_mul_f32_e32 v159, v9, v136
	v_fma_f32 v167, -v209, v159, v167
	v_bfe_u32 v159, v167, 16, 1
	v_add3_u32 v167, v167, v159, s43
	global_store_short_d16_hi v[146:147], v167, off offset:2048
	v_mul_f32_e32 v160, v10, v135
	v_fma_f32 v168, -v209, v160, v168
	v_bfe_u32 v160, v168, 16, 1
	v_add3_u32 v168, v168, v160, s43
	global_store_short_d16_hi v[148:149], v168, off
	v_mul_f32_e32 v150, v11, v134
	v_fma_f32 v169, -v209, v150, v169
	v_bfe_u32 v150, v169, 16, 1
	v_add3_u32 v169, v169, v150, s43
	global_store_short_d16_hi v[148:149], v169, off offset:2048
	v_mul_f32_e32 v158, v120, v137
	v_fma_f32 v170, -v209, v158, v170
	v_bfe_u32 v158, v170, 16, 1
	v_add3_u32 v170, v170, v158, s43
	global_store_short_d16_hi v[146:147], v170, off offset:64
	v_mul_f32_e32 v159, v121, v136
	v_fma_f32 v171, -v209, v159, v171
	v_bfe_u32 v159, v171, 16, 1
	v_add3_u32 v171, v171, v159, s43
	global_store_short_d16_hi v[146:147], v171, off offset:2112
	v_mul_f32_e32 v160, v122, v135
	v_fma_f32 v172, -v209, v160, v172
	v_bfe_u32 v160, v172, 16, 1
	v_add3_u32 v172, v172, v160, s43
	global_store_short_d16_hi v[148:149], v172, off offset:64
	v_mul_f32_e32 v150, v123, v134
	v_fma_f32 v173, -v209, v150, v173
	v_bfe_u32 v150, v173, 16, 1
	v_add3_u32 v173, v173, v150, s43
	global_store_short_d16_hi v[148:149], v173, off offset:2112
	v_mul_f32_e32 v158, v104, v137
	v_fma_f32 v174, -v209, v158, v174
	v_bfe_u32 v158, v174, 16, 1
	v_add3_u32 v174, v174, v158, s43
	global_store_short_d16_hi v[146:147], v174, off offset:128
	v_mul_f32_e32 v159, v105, v136
	v_fma_f32 v175, -v209, v159, v175
	v_bfe_u32 v159, v175, 16, 1
	v_add3_u32 v175, v175, v159, s43
	global_store_short_d16_hi v[146:147], v175, off offset:2176
	v_mul_f32_e32 v160, v106, v135
	v_fma_f32 v176, -v209, v160, v176
	v_bfe_u32 v160, v176, 16, 1
	v_add3_u32 v176, v176, v160, s43
	global_store_short_d16_hi v[148:149], v176, off offset:128
	v_mul_f32_e32 v150, v107, v134
	v_fma_f32 v177, -v209, v150, v177
	v_bfe_u32 v150, v177, 16, 1
	v_add3_u32 v177, v177, v150, s43
	global_store_short_d16_hi v[148:149], v177, off offset:2176
	v_mul_f32_e32 v158, v88, v137
	v_fma_f32 v178, -v209, v158, v178
	v_bfe_u32 v158, v178, 16, 1
	v_add3_u32 v178, v178, v158, s43
	global_store_short_d16_hi v[146:147], v178, off offset:192
	v_mul_f32_e32 v159, v89, v136
	v_fma_f32 v179, -v209, v159, v179
	v_bfe_u32 v159, v179, 16, 1
	v_add3_u32 v179, v179, v159, s43
	global_store_short_d16_hi v[146:147], v179, off offset:2240
	v_mul_f32_e32 v160, v90, v135
	v_fma_f32 v180, -v209, v160, v180
	v_bfe_u32 v160, v180, 16, 1
	v_add3_u32 v180, v180, v160, s43
	global_store_short_d16_hi v[148:149], v180, off offset:192
	v_mul_f32_e32 v150, v91, v134
	v_fma_f32 v181, -v209, v150, v181
	v_bfe_u32 v150, v181, 16, 1
	v_add3_u32 v181, v181, v150, s43
	global_store_short_d16_hi v[148:149], v181, off offset:2240
	v_mul_f32_e32 v158, v72, v137
	v_fma_f32 v182, -v209, v158, v182
	v_bfe_u32 v158, v182, 16, 1
	v_add3_u32 v182, v182, v158, s43
	global_store_short_d16_hi v[146:147], v182, off offset:256
	v_mul_f32_e32 v159, v73, v136
	v_fma_f32 v183, -v209, v159, v183
	v_bfe_u32 v159, v183, 16, 1
	v_add3_u32 v183, v183, v159, s43
	global_store_short_d16_hi v[146:147], v183, off offset:2304
	v_mul_f32_e32 v160, v74, v135
	v_fma_f32 v184, -v209, v160, v184
	v_bfe_u32 v160, v184, 16, 1
	v_add3_u32 v184, v184, v160, s43
	global_store_short_d16_hi v[148:149], v184, off offset:256
	v_mul_f32_e32 v150, v75, v134
	v_fma_f32 v185, -v209, v150, v185
	v_bfe_u32 v150, v185, 16, 1
	v_add3_u32 v185, v185, v150, s43
	global_store_short_d16_hi v[148:149], v185, off offset:2304
	v_mul_f32_e32 v158, v56, v137
	v_fma_f32 v186, -v209, v158, v186
	v_bfe_u32 v158, v186, 16, 1
	v_add3_u32 v186, v186, v158, s43
	global_store_short_d16_hi v[146:147], v186, off offset:320
	v_mul_f32_e32 v159, v57, v136
	v_fma_f32 v187, -v209, v159, v187
	v_bfe_u32 v159, v187, 16, 1
	v_add3_u32 v187, v187, v159, s43
	global_store_short_d16_hi v[146:147], v187, off offset:2368
	v_mul_f32_e32 v160, v58, v135
	v_fma_f32 v188, -v209, v160, v188
	v_bfe_u32 v160, v188, 16, 1
	v_add3_u32 v188, v188, v160, s43
	global_store_short_d16_hi v[148:149], v188, off offset:320
	v_mul_f32_e32 v150, v59, v134
	v_fma_f32 v189, -v209, v150, v189
	v_bfe_u32 v150, v189, 16, 1
	v_add3_u32 v189, v189, v150, s43
	global_store_short_d16_hi v[148:149], v189, off offset:2368
	v_mul_f32_e32 v158, v40, v137
	v_fma_f32 v190, -v209, v158, v190
	v_bfe_u32 v158, v190, 16, 1
	v_add3_u32 v190, v190, v158, s43
	global_store_short_d16_hi v[146:147], v190, off offset:384
	v_mul_f32_e32 v159, v41, v136
	v_fma_f32 v191, -v209, v159, v191
	v_bfe_u32 v159, v191, 16, 1
	v_add3_u32 v191, v191, v159, s43
	global_store_short_d16_hi v[146:147], v191, off offset:2432
	v_mul_f32_e32 v160, v42, v135
	v_fma_f32 v192, -v209, v160, v192
	v_bfe_u32 v160, v192, 16, 1
	v_add3_u32 v192, v192, v160, s43
	global_store_short_d16_hi v[148:149], v192, off offset:384
	v_mul_f32_e32 v150, v43, v134
	v_fma_f32 v193, -v209, v150, v193
	v_bfe_u32 v150, v193, 16, 1
	v_add3_u32 v193, v193, v150, s43
	global_store_short_d16_hi v[148:149], v193, off offset:2432
	v_mul_f32_e32 v158, v24, v137
	v_fma_f32 v194, -v209, v158, v194
	v_bfe_u32 v158, v194, 16, 1
	v_add3_u32 v194, v194, v158, s43
	global_store_short_d16_hi v[146:147], v194, off offset:448
	v_mul_f32_e32 v159, v25, v136
	v_fma_f32 v195, -v209, v159, v195
	v_bfe_u32 v159, v195, 16, 1
	v_add3_u32 v195, v195, v159, s43
	global_store_short_d16_hi v[146:147], v195, off offset:2496
	v_mul_f32_e32 v160, v26, v135
	v_fma_f32 v196, -v209, v160, v196
	v_bfe_u32 v160, v196, 16, 1
	v_add3_u32 v196, v196, v160, s43
	global_store_short_d16_hi v[148:149], v196, off offset:448
	v_mul_f32_e32 v150, v27, v134
	v_fma_f32 v197, -v209, v150, v197
	v_bfe_u32 v150, v197, 16, 1
	v_add3_u32 v197, v197, v150, s43
	global_store_short_d16_hi v[148:149], v197, off offset:2496
	v_lshl_add_u64 v[146:147], v[146:147], 0, s[98:99]
	s_waitcnt vmcnt(32)
	v_lshl_add_u64 v[148:149], v[146:147], 0, s[100:101]
	v_mul_f32_e32 v158, v12, v133
	v_fma_f32 v198, -v209, v158, v198
	v_bfe_u32 v158, v198, 16, 1
	v_add3_u32 v198, v198, v158, s43
	global_store_short_d16_hi v[146:147], v198, off
	v_mul_f32_e32 v159, v13, v132
	v_fma_f32 v199, -v209, v159, v199
	v_bfe_u32 v159, v199, 16, 1
	v_add3_u32 v199, v199, v159, s43
	global_store_short_d16_hi v[146:147], v199, off offset:2048
	v_mul_f32_e32 v160, v14, v131
	v_fma_f32 v200, -v209, v160, v200
	v_bfe_u32 v160, v200, 16, 1
	v_add3_u32 v200, v200, v160, s43
	global_store_short_d16_hi v[148:149], v200, off
	v_mul_f32_e32 v150, v15, v130
	v_fma_f32 v201, -v209, v150, v201
	v_bfe_u32 v150, v201, 16, 1
	v_add3_u32 v201, v201, v150, s43
	global_store_short_d16_hi v[148:149], v201, off offset:2048
	v_mul_f32_e32 v158, v124, v133
	v_fma_f32 v202, -v209, v158, v202
	v_bfe_u32 v158, v202, 16, 1
	v_add3_u32 v202, v202, v158, s43
	global_store_short_d16_hi v[146:147], v202, off offset:64
	v_mul_f32_e32 v159, v125, v132
	v_fma_f32 v203, -v209, v159, v203
	v_bfe_u32 v159, v203, 16, 1
	v_add3_u32 v203, v203, v159, s43
	global_store_short_d16_hi v[146:147], v203, off offset:2112
	v_mul_f32_e32 v160, v126, v131
	v_fma_f32 v204, -v209, v160, v204
	v_bfe_u32 v160, v204, 16, 1
	v_add3_u32 v204, v204, v160, s43
	global_store_short_d16_hi v[148:149], v204, off offset:64
	v_mul_f32_e32 v150, v127, v130
	v_fma_f32 v205, -v209, v150, v205
	v_bfe_u32 v150, v205, 16, 1
	v_add3_u32 v205, v205, v150, s43
	global_store_short_d16_hi v[148:149], v205, off offset:2112
	v_mul_f32_e32 v158, v108, v133
	v_fma_f32 v240, -v209, v158, v240
	v_bfe_u32 v158, v240, 16, 1
	v_add3_u32 v240, v240, v158, s43
	global_store_short_d16_hi v[146:147], v240, off offset:128
	v_mul_f32_e32 v159, v109, v132
	v_fma_f32 v241, -v209, v159, v241
	v_bfe_u32 v159, v241, 16, 1
	v_add3_u32 v241, v241, v159, s43
	global_store_short_d16_hi v[146:147], v241, off offset:2176
	v_mul_f32_e32 v160, v110, v131
	v_fma_f32 v242, -v209, v160, v242
	v_bfe_u32 v160, v242, 16, 1
	v_add3_u32 v242, v242, v160, s43
	global_store_short_d16_hi v[148:149], v242, off offset:128
	v_mul_f32_e32 v150, v111, v130
	v_fma_f32 v243, -v209, v150, v243
	v_bfe_u32 v150, v243, 16, 1
	v_add3_u32 v243, v243, v150, s43
	global_store_short_d16_hi v[148:149], v243, off offset:2176
	v_mul_f32_e32 v158, v92, v133
	v_fma_f32 v244, -v209, v158, v244
	v_bfe_u32 v158, v244, 16, 1
	v_add3_u32 v244, v244, v158, s43
	global_store_short_d16_hi v[146:147], v244, off offset:192
	v_mul_f32_e32 v159, v93, v132
	v_fma_f32 v245, -v209, v159, v245
	v_bfe_u32 v159, v245, 16, 1
	v_add3_u32 v245, v245, v159, s43
	global_store_short_d16_hi v[146:147], v245, off offset:2240
	v_mul_f32_e32 v160, v94, v131
	v_fma_f32 v246, -v209, v160, v246
	v_bfe_u32 v160, v246, 16, 1
	v_add3_u32 v246, v246, v160, s43
	global_store_short_d16_hi v[148:149], v246, off offset:192
	v_mul_f32_e32 v150, v95, v130
	v_fma_f32 v247, -v209, v150, v247
	v_bfe_u32 v150, v247, 16, 1
	v_add3_u32 v247, v247, v150, s43
	global_store_short_d16_hi v[148:149], v247, off offset:2240
	v_mul_f32_e32 v158, v76, v133
	v_fma_f32 v248, -v209, v158, v248
	v_bfe_u32 v158, v248, 16, 1
	v_add3_u32 v248, v248, v158, s43
	global_store_short_d16_hi v[146:147], v248, off offset:256
	v_mul_f32_e32 v159, v77, v132
	v_fma_f32 v249, -v209, v159, v249
	v_bfe_u32 v159, v249, 16, 1
	v_add3_u32 v249, v249, v159, s43
	global_store_short_d16_hi v[146:147], v249, off offset:2304
	v_mul_f32_e32 v160, v78, v131
	v_fma_f32 v250, -v209, v160, v250
	v_bfe_u32 v160, v250, 16, 1
	v_add3_u32 v250, v250, v160, s43
	global_store_short_d16_hi v[148:149], v250, off offset:256
	v_mul_f32_e32 v150, v79, v130
	v_fma_f32 v251, -v209, v150, v251
	v_bfe_u32 v150, v251, 16, 1
	v_add3_u32 v251, v251, v150, s43
	global_store_short_d16_hi v[148:149], v251, off offset:2304
	v_mul_f32_e32 v158, v60, v133
	v_fma_f32 v252, -v209, v158, v252
	v_bfe_u32 v158, v252, 16, 1
	v_add3_u32 v252, v252, v158, s43
	global_store_short_d16_hi v[146:147], v252, off offset:320
	v_mul_f32_e32 v159, v61, v132
	v_fma_f32 v253, -v209, v159, v253
	v_bfe_u32 v159, v253, 16, 1
	v_add3_u32 v253, v253, v159, s43
	global_store_short_d16_hi v[146:147], v253, off offset:2368
	v_mul_f32_e32 v160, v62, v131
	v_fma_f32 v254, -v209, v160, v254
	v_bfe_u32 v160, v254, 16, 1
	v_add3_u32 v254, v254, v160, s43
	global_store_short_d16_hi v[148:149], v254, off offset:320
	v_mul_f32_e32 v150, v63, v130
	v_fma_f32 v255, -v209, v150, v255
	v_bfe_u32 v150, v255, 16, 1
	v_add3_u32 v255, v255, v150, s43
	global_store_short_d16_hi v[148:149], v255, off offset:2368
	v_mul_f32_e32 v158, v44, v133
	v_fma_f32 v232, -v209, v158, v232
	v_bfe_u32 v158, v232, 16, 1
	v_add3_u32 v232, v232, v158, s43
	global_store_short_d16_hi v[146:147], v232, off offset:384
	v_mul_f32_e32 v159, v45, v132
	v_fma_f32 v233, -v209, v159, v233
	v_bfe_u32 v159, v233, 16, 1
	v_add3_u32 v233, v233, v159, s43
	global_store_short_d16_hi v[146:147], v233, off offset:2432
	v_mul_f32_e32 v160, v46, v131
	v_fma_f32 v234, -v209, v160, v234
	v_bfe_u32 v160, v234, 16, 1
	v_add3_u32 v234, v234, v160, s43
	global_store_short_d16_hi v[148:149], v234, off offset:384
	v_mul_f32_e32 v150, v47, v130
	v_fma_f32 v235, -v209, v150, v235
	v_bfe_u32 v150, v235, 16, 1
	v_add3_u32 v235, v235, v150, s43
	global_store_short_d16_hi v[148:149], v235, off offset:2432
	v_mul_f32_e32 v158, v28, v133
	v_fma_f32 v154, -v209, v158, v154
	v_bfe_u32 v158, v154, 16, 1
	v_add3_u32 v154, v154, v158, s43
	global_store_short_d16_hi v[146:147], v154, off offset:448
	v_mul_f32_e32 v159, v29, v132
	v_fma_f32 v155, -v209, v159, v155
	v_bfe_u32 v159, v155, 16, 1
	v_add3_u32 v155, v155, v159, s43
	global_store_short_d16_hi v[146:147], v155, off offset:2496
	v_mul_f32_e32 v160, v30, v131
	v_fma_f32 v156, -v209, v160, v156
	v_bfe_u32 v160, v156, 16, 1
	v_add3_u32 v156, v156, v160, s43
	global_store_short_d16_hi v[148:149], v156, off offset:448
	v_mul_f32_e32 v150, v31, v130
	v_fma_f32 v157, -v209, v150, v157
	v_bfe_u32 v150, v157, 16, 1
	v_add3_u32 v157, v157, v150, s43
	global_store_short_d16_hi v[148:149], v157, off offset:2496
	s_branch .LBB0_901
